# phase-3 scan and decay prefix: loads batched and store-ack waits removed; final norm gains hoisted and next row prefetched; GLA state-phase value loads batched; dilated loop-top store waits removed
# speedup vs baseline: 1.0228x; 1.0083x over previous
; __global__ void __launch_bounds__(NTHR, 2) fwd_mega(Args args) {
;     ...
;             if (vcu == G - 1 && tid < 32) { const int b_ = tid >> 3, h_ = tid & 7; float acc = 0.f;
;                 for (int cc = 0; cc < 64; ++cc) { OFFS[(b_ * 64 + cc) * 8 + h_] = acc; acc += TOTB[(b_ * 64 + cc) * 8 + h_]; } }
.LBB0_452:
	v_add_u32_e32 v4, s1, v0
	v_ashrrev_i32_e32 v5, 31, v4
	v_lshlrev_b64 v[6:7], 2, v[4:5]
	v_lshl_add_u64 v[8:9], s[24:25], 0, v[6:7]
	v_lshl_add_u64 v[6:7], s[90:91], 0, v[6:7]
	s_waitcnt lgkmcnt(0)
	global_load_dword v66, v[6:7], off
	global_load_dword v67, v[6:7], off offset:32
	global_load_dword v68, v[6:7], off offset:64
	global_load_dword v69, v[6:7], off offset:96
	global_load_dword v70, v[6:7], off offset:128
	global_load_dword v71, v[6:7], off offset:160
	global_load_dword v72, v[6:7], off offset:192
	global_load_dword v73, v[6:7], off offset:224
	s_add_i32 s1, s1, 64
	s_cmpk_lg_i32 s1, 0x200
	s_waitcnt vmcnt(0)
	global_store_dword v[8:9], v2, off
	v_add_f32_e32 v2, v2, v66
	global_store_dword v[8:9], v2, off offset:32
	v_add_f32_e32 v2, v2, v67
	global_store_dword v[8:9], v2, off offset:64
	v_add_f32_e32 v2, v2, v68
	global_store_dword v[8:9], v2, off offset:96
	v_add_f32_e32 v2, v2, v69
	global_store_dword v[8:9], v2, off offset:128
	v_add_f32_e32 v2, v2, v70
	global_store_dword v[8:9], v2, off offset:160
	v_add_f32_e32 v2, v2, v71
	global_store_dword v[8:9], v2, off offset:192
	v_add_f32_e32 v2, v2, v72
	global_store_dword v[8:9], v2, off offset:224
	v_add_f32_e32 v2, v2, v73
	s_cbranch_scc1 .LBB0_452

; DI unsigned pk2(float lo, float hi) { return cvtpk(lo, hi); }
; __global__ void __launch_bounds__(NTHR, 2) fwd_mega(Args args) {
;     ...
;                     for (int q = 0; q < 2; ++q) { const int pe = pb + tid + 288 * q; ok[q] = pe < 16 * 9216; const int pp = ok[q] ? pe : 0; const int bh = pp / 9216, vk = pp - 9216 * bh, k0 = 2 * (vk % 48);
;                         sp[q] = (unsigned*)SC + (size_t)bh * 128 * 9216 + vk; dp[q] = DEC + (size_t)bh * 128 * 96 + k0; st[q][0] = 0.f; st[q][1] = 0.f; }
;                     for (int n = 0; n < 128; n += 8) { unsigned tv[2][8]; float d0[2][8], d1[2][8];
; #pragma unroll
;                         for (int q = 0; q < 2; ++q)
; #pragma unroll
;                             for (int jj = 0; jj < 8; ++jj) { tv[q][jj] = sp[q][(size_t)(n + jj) * 9216]; d0[q][jj] = dp[q][(n + jj) * 96]; d1[q][jj] = dp[q][(n + jj) * 96 + 1]; }
; #pragma unroll
;                         for (int q = 0; q < 2; ++q) if (ok[q]) {
; #pragma unroll
;                             for (int jj = 0; jj < 8; ++jj) { sp[q][(size_t)(n + jj) * 9216] = pk2(st[q][0], st[q][1]);
;                                 st[q][0] = st[q][0] * d0[q][jj] + bflo(tv[q][jj]); st[q][1] = st[q][1] * d1[q][jj] + bfhi(tv[q][jj]); } } } }
.LBB0_463:
	v_lshl_add_u64 v[12:13], s[74:75], 0, v[6:7]
	s_nop 0
	v_add_co_u32_e32 v14, vcc, 0x31a00000, v12
	s_nop 1
	v_addc_co_u32_e32 v15, vcc, 0, v13, vcc
	global_load_dword v0, v[14:15], off
	v_lshl_add_u64 v[14:15], s[74:75], 0, v[4:5]
	v_add_co_u32_e32 v28, vcc, 0x200000, v14
	s_nop 1
	v_addc_co_u32_e32 v29, vcc, 0, v15, vcc
	v_add_co_u32_e32 v16, vcc, 0x31a09000, v12
	global_load_dwordx2 v[14:15], v[28:29], off
	s_nop 0
	v_addc_co_u32_e32 v17, vcc, 0, v13, vcc
	v_add_co_u32_e32 v18, vcc, 0x31a12000, v12
	global_load_dword v36, v[16:17], off
	s_nop 0
	global_load_dwordx2 v[16:17], v[28:29], off offset:384
	v_addc_co_u32_e32 v19, vcc, 0, v13, vcc
	global_load_dword v37, v[18:19], off
	global_load_dwordx2 v[20:21], v[28:29], off offset:768
	v_add_co_u32_e32 v18, vcc, 0x31a1b000, v12
	s_nop 1
	v_addc_co_u32_e32 v19, vcc, 0, v13, vcc
	v_add_co_u32_e32 v22, vcc, 0x31a24000, v12
	global_load_dword v38, v[18:19], off
	s_nop 0
	global_load_dwordx2 v[18:19], v[28:29], off offset:1152
	v_addc_co_u32_e32 v23, vcc, 0, v13, vcc
	v_add_co_u32_e32 v24, vcc, 0x31a2d000, v12
	global_load_dword v39, v[22:23], off
	s_nop 0
	global_load_dwordx2 v[22:23], v[28:29], off offset:1536
	v_addc_co_u32_e32 v25, vcc, 0, v13, vcc
	v_add_co_u32_e32 v26, vcc, 0x31a36000, v12
	global_load_dword v40, v[24:25], off
	s_nop 0
	global_load_dwordx2 v[24:25], v[28:29], off offset:1920
	v_addc_co_u32_e32 v27, vcc, 0, v13, vcc
	v_add_co_u32_e32 v32, vcc, 0x31a3f000, v12
	global_load_dword v41, v[26:27], off
	s_nop 0
	global_load_dwordx2 v[26:27], v[28:29], off offset:2304
	v_addc_co_u32_e32 v33, vcc, 0, v13, vcc
	global_load_dword v42, v[32:33], off
	s_nop 0
	global_load_dwordx2 v[28:29], v[28:29], off offset:2688
	s_and_saveexec_b64 s[14:15], s[40:41]
	s_cbranch_execz .Lscan_skip_col1
	v_lshl_add_u64 v[46:47], s[74:75], 0, v[8:9]
	v_add_co_u32_e32 v32, vcc, 0x31a3f000, v46
	s_mov_b32 s5, 0x31a24000
	s_nop 0
	v_addc_co_u32_e32 v33, vcc, 0, v47, vcc
	v_add_co_u32_e32 v34, vcc, 0x31a36000, v46
	v_lshl_add_u64 v[44:45], s[74:75], 0, v[2:3]
	s_nop 0
	v_addc_co_u32_e32 v35, vcc, 0, v47, vcc
	v_add_co_u32_e32 v48, vcc, 0x31a2d000, v46
	v_cvt_pk_bf16_f32 v59, v30, v31
	s_nop 0
	v_addc_co_u32_e32 v49, vcc, 0, v47, vcc
	v_add_co_u32_e32 v50, vcc, s5, v46
	s_mov_b32 s5, 0x31a1b000
	s_nop 0
	v_addc_co_u32_e32 v51, vcc, 0, v47, vcc
	v_add_co_u32_e32 v52, vcc, s5, v46
	s_mov_b32 s5, 0x31a12000
	s_nop 0
	v_addc_co_u32_e32 v53, vcc, 0, v47, vcc
	v_add_co_u32_e32 v54, vcc, s5, v46
	s_mov_b32 s5, 0x31a09000
	s_nop 0
	v_addc_co_u32_e32 v55, vcc, 0, v47, vcc
	v_add_co_u32_e32 v56, vcc, s5, v46
	s_mov_b32 s5, 0x31a00000
	s_nop 0
	v_addc_co_u32_e32 v57, vcc, 0, v47, vcc
	v_add_co_u32_e32 v46, vcc, s5, v46
	global_load_dword v64, v[54:55], off
	s_nop 0
	v_addc_co_u32_e32 v47, vcc, 0, v47, vcc
	global_load_dword v58, v[46:47], off
	s_mov_b32 s5, 0x200000
	v_add_co_u32_e32 v44, vcc, s5, v44
	global_load_dword v43, v[32:33], off
	global_load_dword v60, v[34:35], off
	global_load_dword v61, v[48:49], off
	global_load_dword v65, v[56:57], off
	v_addc_co_u32_e32 v45, vcc, 0, v45, vcc
	global_load_dwordx2 v[66:67], v[44:45], off
	global_load_dwordx2 v[68:69], v[44:45], off offset:384
	global_load_dwordx2 v[70:71], v[44:45], off offset:768
	global_load_dwordx2 v[72:73], v[44:45], off offset:1152
	global_load_dwordx2 v[74:75], v[44:45], off offset:1536
	global_load_dwordx2 v[76:77], v[44:45], off offset:1920
	global_load_dwordx2 v[78:79], v[44:45], off offset:2304
	global_load_dwordx2 v[80:81], v[44:45], off offset:2688
	global_store_dword v[46:47], v59, off
	global_load_dword v62, v[50:51], off
	global_load_dword v63, v[52:53], off
	s_waitcnt vmcnt(0)
	v_lshlrev_b32_e32 v46, 16, v58
	v_and_b32_e32 v47, 0xffff0000, v58
	s_nop 0
	v_pk_fma_f32 v[30:31], v[30:31], v[66:67], v[46:47]
	s_nop 0
	v_cvt_pk_bf16_f32 v46, v30, v31
	global_store_dword v[56:57], v46, off
	v_lshlrev_b32_e32 v46, 16, v65
	v_and_b32_e32 v47, 0xffff0000, v65
	s_nop 0
	v_pk_fma_f32 v[30:31], v[30:31], v[68:69], v[46:47]
	s_nop 0
	v_cvt_pk_bf16_f32 v46, v30, v31
	global_store_dword v[54:55], v46, off
	v_lshlrev_b32_e32 v46, 16, v64
	v_and_b32_e32 v47, 0xffff0000, v64
	s_nop 0
	v_pk_fma_f32 v[30:31], v[30:31], v[70:71], v[46:47]
	s_nop 0
	v_cvt_pk_bf16_f32 v46, v30, v31
	global_store_dword v[52:53], v46, off
	v_lshlrev_b32_e32 v46, 16, v63
	v_and_b32_e32 v47, 0xffff0000, v63
	s_nop 0
	v_pk_fma_f32 v[30:31], v[30:31], v[72:73], v[46:47]
	s_nop 0
	v_cvt_pk_bf16_f32 v46, v30, v31
	global_store_dword v[50:51], v46, off
	v_lshlrev_b32_e32 v46, 16, v62
	v_and_b32_e32 v47, 0xffff0000, v62
	s_nop 0
	v_pk_fma_f32 v[30:31], v[30:31], v[74:75], v[46:47]
	s_nop 0
	v_cvt_pk_bf16_f32 v46, v30, v31
	global_store_dword v[48:49], v46, off
	v_lshlrev_b32_e32 v46, 16, v61
	v_and_b32_e32 v47, 0xffff0000, v61
	s_nop 0
	v_pk_fma_f32 v[30:31], v[30:31], v[76:77], v[46:47]
	s_nop 0
	v_cvt_pk_bf16_f32 v46, v30, v31
	global_store_dword v[34:35], v46, off
	v_lshlrev_b32_e32 v34, 16, v60
	v_and_b32_e32 v35, 0xffff0000, v60
	s_nop 0
	v_pk_fma_f32 v[30:31], v[30:31], v[78:79], v[34:35]
	s_nop 0
	v_cvt_pk_bf16_f32 v34, v30, v31
	global_store_dword v[32:33], v34, off
	v_lshlrev_b32_e32 v32, 16, v43
	v_and_b32_e32 v33, 0xffff0000, v43
	s_nop 0
	v_pk_fma_f32 v[30:31], v[30:31], v[80:81], v[32:33]
; DI unsigned pk2(float lo, float hi) { return cvtpk(lo, hi); }
; __global__ void __launch_bounds__(NTHR, 2) fwd_mega(Args args) {
;     ...
;                         for (int q = 0; q < 2; ++q) if (ok[q]) {
; #pragma unroll
;                             for (int jj = 0; jj < 8; ++jj) { sp[q][(size_t)(n + jj) * 9216] = pk2(st[q][0], st[q][1]);
;                                 st[q][0] = st[q][0] * d0[q][jj] + bflo(tv[q][jj]); st[q][1] = st[q][1] * d1[q][jj] + bfhi(tv[q][jj]); } } } }
.LBB0_465:
	s_or_b64 exec, exec, s[14:15]
	s_and_saveexec_b64 s[10:11], s[42:43]
	s_cbranch_execz .LBB0_462
	s_mov_b64 s[6:7], 0x31a00000
	v_lshl_add_u64 v[32:33], v[12:13], 0, s[6:7]
	v_cvt_pk_bf16_f32 v43, v10, v11
	global_store_dword v[32:33], v43, off
	s_nop 0
	v_lshlrev_b32_e32 v32, 16, v0
	v_and_b32_e32 v33, 0xffff0000, v0
	s_mov_b64 s[6:7], 0x31a09000
	v_pk_fma_f32 v[10:11], v[10:11], v[14:15], v[32:33]
	v_lshlrev_b32_e32 v14, 16, v36
	v_and_b32_e32 v15, 0xffff0000, v36
	v_lshl_add_u64 v[34:35], v[12:13], 0, s[6:7]
	s_mov_b64 s[6:7], 0x31a12000
	v_cvt_pk_bf16_f32 v0, v10, v11
	v_pk_fma_f32 v[10:11], v[10:11], v[16:17], v[14:15]
	v_lshlrev_b32_e32 v14, 16, v37
	v_and_b32_e32 v15, 0xffff0000, v37
	v_lshl_add_u64 v[44:45], v[12:13], 0, s[6:7]
	s_mov_b64 s[6:7], 0x31a1b000
	global_store_dword v[34:35], v0, off
	v_cvt_pk_bf16_f32 v0, v10, v11
	v_pk_fma_f32 v[10:11], v[10:11], v[20:21], v[14:15]
	v_lshlrev_b32_e32 v14, 16, v38
	v_and_b32_e32 v15, 0xffff0000, v38
	v_lshl_add_u64 v[46:47], v[12:13], 0, s[6:7]
	s_mov_b64 s[6:7], 0x31a24000
	global_store_dword v[44:45], v0, off
	v_cvt_pk_bf16_f32 v0, v10, v11
	v_pk_fma_f32 v[10:11], v[10:11], v[18:19], v[14:15]
	v_lshlrev_b32_e32 v14, 16, v39
	v_and_b32_e32 v15, 0xffff0000, v39
	v_lshl_add_u64 v[48:49], v[12:13], 0, s[6:7]
	s_mov_b64 s[6:7], 0x31a2d000
	global_store_dword v[46:47], v0, off
	v_cvt_pk_bf16_f32 v0, v10, v11
	v_pk_fma_f32 v[10:11], v[10:11], v[22:23], v[14:15]
	v_lshlrev_b32_e32 v14, 16, v40
	v_and_b32_e32 v15, 0xffff0000, v40
	v_lshl_add_u64 v[50:51], v[12:13], 0, s[6:7]
	s_mov_b64 s[6:7], 0x31a36000
	global_store_dword v[48:49], v0, off
	v_cvt_pk_bf16_f32 v0, v10, v11
	v_pk_fma_f32 v[10:11], v[10:11], v[24:25], v[14:15]
	v_lshlrev_b32_e32 v14, 16, v41
	v_and_b32_e32 v15, 0xffff0000, v41
	v_lshl_add_u64 v[52:53], v[12:13], 0, s[6:7]
	s_mov_b64 s[6:7], 0x31a3f000
	global_store_dword v[50:51], v0, off
	v_cvt_pk_bf16_f32 v0, v10, v11
	v_pk_fma_f32 v[10:11], v[10:11], v[26:27], v[14:15]
	v_lshl_add_u64 v[12:13], v[12:13], 0, s[6:7]
	global_store_dword v[52:53], v0, off
	v_cvt_pk_bf16_f32 v0, v10, v11
	global_store_dword v[12:13], v0, off
	v_lshlrev_b32_e32 v12, 16, v42
	v_and_b32_e32 v13, 0xffff0000, v42
	v_pk_fma_f32 v[10:11], v[10:11], v[28:29], v[12:13]
	s_branch .LBB0_462
.Lscan_skip_col1:
	s_waitcnt vmcnt(0)
	s_branch .LBB0_465

; #define LAS __attribute__((address_space(3)))
; #define MFMA32(a, b, c) __builtin_amdgcn_mfma_f32_32x32x16_bf16((a), (b), (c), 0, 0, 0)
; DI unsigned pk2(float lo, float hi) { return cvtpk(lo, hi); }
; template <int PH>
; DI void gla_unit(LAS char* lds, int unit, const bf16* PROJ, const float* W2, const float* gb, bf16* SC, float* DEC, const float* cnorm, bf16* MIXED, bf16* QG, bf16* KG) {
;     ...
;         { const bf16* kp = PROJ + (row0 + t) * PROJP + O_KC + 96 * h + 12 * kg; const bf16* qp = PROJ + (row0 + t) * PROJP + O_QC + 96 * h + 12 * kg;
; #pragma unroll
;           for (int j = 0; j < 3; ++j) { kv[j] = *(const u32x2*)(kp + 4 * j); qv[j] = *(const u32x2*)(qp + 4 * j); } }
; #pragma unroll
;         for (int j = 0; j < 3; ++j) { const int c = tid + NTHR * j, tt = c / 24, ch = c - 24 * tt;
;             *(LAS u32x4*)(lds + G_VT + tt * PV + ch * 16) = *(const u32x4*)(PROJ + (row0 + tt) * PROJP + O_VC + 192 * h + 8 * ch); }
;         if (w < 3) {
;             const int k = 32 * w + r32;
;             bf16x8 bw; { u32x4 pw;
; #pragma unroll
;                 for (int j = 0; j < 4; ++j) pw[j] = pk2(W2[(8 * hi + 2 * j) * 384 + 96 * h + k], W2[(8 * hi + 2 * j + 1) * 384 + 96 * h + k]);
;                 bw = __builtin_bit_cast(bf16x8, pw); }
;             const float gbias = gb[96 * h + k];
;             float carry = 0.f;
; #pragma unroll
;             for (int mi = 0; mi < 2; ++mi) {
;                 const bf16x8 ga = *(const bf16x8*)(PROJ + (row0 + 32 * mi + r32) * PROJP + O_GL + 8 * hi);
;                 f32x16 d;
; #pragma unroll
;                 for (int r = 0; r < 16; ++r) d[r] = 0.f;
;                 d = MFMA32(ga, bw, d);
.LBB0_489:
	s_ashr_i32 s10, s6, 9
	s_bfe_u32 s21, s6, 0x70002
	s_waitcnt vmcnt(0)
	v_mov_b32_e32 v34, v227
	s_ashr_i32 s11, s10, 31
	s_lshl_b64 s[10:11], s[10:11], 13
	s_lshl_b32 s12, s21, 6
	v_ashrrev_i32_e32 v40, 3, v34
	s_or_b32 s10, s10, s12
	v_ashrrev_i32_e32 v41, 31, v40
	v_lshl_add_u64 v[42:43], s[10:11], 0, v[40:41]
	v_mov_b64_e32 v[6:7], s[80:81]
	s_and_b32 s22, s6, 3
	v_mad_u64_u32 v[2:3], s[12:13], v42, s0, v[6:7]
	v_and_b32_e32 v35, 7, v34
	s_mul_i32 s12, s22, 0x60
	v_mad_i32_i24 v3, v43, s0, v3
	s_lshl_b32 s30, s12, 1
	v_mul_u32_u24_e32 v46, 12, v35
	v_lshl_add_u64 v[2:3], v[2:3], 0, s[30:31]
	v_lshlrev_b32_e32 v0, 1, v46
	v_lshl_add_u64 v[2:3], v[2:3], 0, v[0:1]
	global_load_dwordx2 v[38:39], v[2:3], off offset:3872
	global_load_dwordx4 v[22:25], v[2:3], off offset:3856
	global_load_dwordx2 v[36:37], v[2:3], off offset:3104
	global_load_dwordx4 v[18:21], v[2:3], off offset:3088
	v_mul_hi_i32 v2, v34, s33
	v_lshrrev_b32_e32 v3, 31, v2
	v_ashrrev_i32_e32 v2, 2, v2
	v_add_u32_e32 v8, v2, v3
	v_ashrrev_i32_e32 v9, 31, v8
	s_movk_i32 s13, 0xffe8
	v_lshl_add_u64 v[2:3], s[10:11], 0, v[8:9]
	v_mad_u64_u32 v[10:11], s[16:17], v8, s13, v[34:35]
	v_mad_u64_u32 v[4:5], s[16:17], v2, s0, v[6:7]
	v_mad_i32_i24 v5, v3, s0, v5
	s_mul_i32 s16, s22, 0x180
	s_mov_b32 s17, s31
	v_lshl_add_u64 v[2:3], v[4:5], 0, s[16:17]
	v_lshlrev_b32_e32 v4, 3, v10
	v_ashrrev_i32_e32 v5, 31, v4
	v_lshl_add_u64 v[2:3], v[4:5], 1, v[2:3]
	v_add_co_u32_e32 v2, vcc, s27, v2
	s_movk_i32 s36, 0x190
	s_nop 0
	v_addc_co_u32_e32 v3, vcc, 0, v3, vcc
	global_load_dwordx4 v[100:103], v[2:3], off offset:528
	v_mul_lo_u32 v8, v8, s36
	v_lshlrev_b32_e32 v9, 4, v10
	v_readlane_b32 s37, v253, 50
	v_readfirstlane_b32 s7, v34
	s_ashr_i32 s7, s7, 6
	v_add3_u32 v112, s37, v8, v9
	v_and_b32_e32 v44, 31, v34
	v_and_b32_e32 v45, 63, v34
	v_bfe_u32 v41, v34, 5, 1
	s_cmp_gt_i32 s7, 2
	v_add_u32_e32 v2, 0x200, v34
	v_mul_hi_i32 v3, v2, s33
	v_lshrrev_b32_e32 v4, 31, v3
	v_ashrrev_i32_e32 v3, 2, v3
	v_add_u32_e32 v8, v3, v4
	v_ashrrev_i32_e32 v9, 31, v8
	v_mad_u64_u32 v[10:11], s[22:23], v8, s13, v[2:3]
	v_lshl_add_u64 v[2:3], s[10:11], 0, v[8:9]
	v_mad_u64_u32 v[4:5], s[22:23], v2, s0, v[6:7]
	v_mad_i32_i24 v5, v3, s0, v5
	v_lshl_add_u64 v[2:3], v[4:5], 0, s[16:17]
	v_lshlrev_b32_e32 v4, 3, v10
	v_ashrrev_i32_e32 v5, 31, v4
	v_lshl_add_u64 v[2:3], v[4:5], 1, v[2:3]
	v_add_co_u32_e32 v2, vcc, s27, v2
	v_mul_lo_u32 v8, v8, s36
	s_nop 0
	v_addc_co_u32_e32 v3, vcc, 0, v3, vcc
	global_load_dwordx4 v[104:107], v[2:3], off offset:528
	v_lshlrev_b32_e32 v9, 4, v10
	v_add3_u32 v113, s37, v8, v9
	v_add_u32_e32 v2, 0x400, v34
	v_mul_hi_i32 v3, v2, s33
	v_lshrrev_b32_e32 v4, 31, v3
	v_ashrrev_i32_e32 v3, 2, v3
	v_add_u32_e32 v8, v3, v4
	v_ashrrev_i32_e32 v9, 31, v8
	v_mad_u64_u32 v[10:11], s[22:23], v8, s13, v[2:3]
	v_lshl_add_u64 v[2:3], s[10:11], 0, v[8:9]
	v_mad_u64_u32 v[4:5], s[22:23], v2, s0, v[6:7]
	v_mad_i32_i24 v5, v3, s0, v5
	v_lshl_add_u64 v[2:3], v[4:5], 0, s[16:17]
	v_lshlrev_b32_e32 v4, 3, v10
	v_ashrrev_i32_e32 v5, 31, v4
	v_lshl_add_u64 v[2:3], v[4:5], 1, v[2:3]
	v_add_co_u32_e32 v2, vcc, 0x1000, v2
	v_mul_lo_u32 v6, v8, s36
	s_nop 0
	v_addc_co_u32_e32 v3, vcc, 0, v3, vcc
	global_load_dwordx4 v[108:111], v[2:3], off offset:528
	v_lshlrev_b32_e32 v7, 4, v10
	v_add3_u32 v114, s37, v6, v7
	s_waitcnt vmcnt(0)
	ds_write_b128 v112, v[100:103]
	ds_write_b128 v113, v[104:107]
	ds_write_b128 v114, v[108:111]
	s_cbranch_scc1 .LBB0_491
	v_lshl_or_b32 v50, s7, 5, v44
	v_add_u32_e32 v10, s12, v50
	s_movk_i32 s12, 0xc00
	v_mad_u32_u24 v2, v41, s12, v10
	v_add_u32_e32 v4, 0x180, v10
	v_ashrrev_i32_e32 v3, 31, v2
	v_mul_u32_u24_e32 v5, 0xc00, v41
	v_lshl_add_u64 v[12:13], v[2:3], 2, s[14:15]
	v_mad_u32_u24 v2, v41, s12, v4
	v_ashrrev_i32_e32 v3, 31, v2
	v_or_b32_e32 v5, 0x300, v5
	v_lshl_add_u64 v[14:15], v[2:3], 2, s[14:15]
	v_add_u32_e32 v2, v10, v5
	v_ashrrev_i32_e32 v3, 31, v2
	v_lshl_add_u64 v[16:17], v[2:3], 2, s[14:15]
	v_add_u32_e32 v2, v4, v5
	v_ashrrev_i32_e32 v3, 31, v2
	v_lshl_add_u64 v[26:27], v[2:3], 2, s[14:15]
	v_mov_b32_e32 v2, 0x600
	v_mad_u32_u24 v5, v41, s12, v2
	v_add_u32_e32 v2, v10, v5
	v_ashrrev_i32_e32 v3, 31, v2
	v_lshl_add_u64 v[28:29], v[2:3], 2, s[14:15]
	v_add_u32_e32 v2, v4, v5
	v_ashrrev_i32_e32 v3, 31, v2
	v_lshl_add_u64 v[30:31], v[2:3], 2, s[14:15]
	v_mov_b32_e32 v2, 0x900
	v_mad_u32_u24 v5, v41, s12, v2
	v_add_u32_e32 v2, v10, v5
	v_ashrrev_i32_e32 v3, 31, v2
	v_lshl_add_u64 v[32:33], v[2:3], 2, s[14:15]
	v_add_u32_e32 v2, v4, v5
	v_ashrrev_i32_e32 v3, 31, v2
	v_or_b32_e32 v51, s10, v44
	v_mov_b64_e32 v[6:7], s[80:81]
	v_lshl_add_u64 v[48:49], v[2:3], 2, s[14:15]
	s_mulk_i32 s11, 0x2100
	v_mad_u64_u32 v[2:3], s[12:13], v51, s0, v[6:7]
	v_add_u32_e32 v3, s11, v3
	v_lshlrev_b32_e32 v8, 4, v41
	v_mov_b32_e32 v9, v1
	v_lshl_add_u64 v[2:3], v[2:3], 0, v[8:9]
	v_add_co_u32_e32 v2, vcc, s27, v2
	v_ashrrev_i32_e32 v11, 31, v10
	s_nop 0
	v_addc_co_u32_e32 v3, vcc, 0, v3, vcc
	global_load_dwordx4 v[2:5], v[2:3], off offset:3600
	s_nop 0
	global_load_dword v12, v[12:13], off
	s_nop 0
	global_load_dword v13, v[14:15], off
	s_nop 0
	global_load_dword v14, v[16:17], off
	global_load_dword v15, v[26:27], off
	s_nop 0
	global_load_dword v16, v[28:29], off
	global_load_dword v17, v[30:31], off
	s_nop 0
	global_load_dword v33, v[32:33], off
	s_nop 0
	global_load_dword v52, v[48:49], off
	v_lshl_add_u64 v[10:11], v[10:11], 2, s[8:9]
	global_load_dword v47, v[10:11], off
	v_xor_b32_e32 v10, 32, v235
	v_add_u32_e32 v11, 64, v236
	v_cmp_lt_i32_e32 vcc, v10, v11
	v_or_b32_e32 v11, 32, v51
	v_mad_u64_u32 v[6:7], s[12:13], v11, s0, v[6:7]
	v_add_u32_e32 v7, s11, v7
	v_lshl_add_u64 v[6:7], v[6:7], 0, v[8:9]
	v_cndmask_b32_e32 v10, v235, v10, vcc
	v_add_co_u32_e32 v6, vcc, s27, v6
	v_lshlrev_b32_e32 v48, 2, v10
	s_nop 0
	v_addc_co_u32_e32 v7, vcc, 0, v7, vcc
	global_load_dwordx4 v[26:29], v[6:7], off offset:3600
	v_lshlrev_b32_e32 v49, 2, v50
	s_waitcnt vmcnt(8)
; #define MFMA32(a, b, c) __builtin_amdgcn_mfma_f32_32x32x16_bf16((a), (b), (c), 0, 0, 0)
; DI float logsig_fast(float x) { return fminf(x, 0.f) - __logf(1.f + __expf(-fabsf(x))); }
; template <int PH>
; DI void gla_unit(LAS char* lds, int unit, const bf16* PROJ, const float* W2, const float* gb, bf16* SC, float* DEC, const float* cnorm, bf16* MIXED, bf16* QG, bf16* KG) {
;     ...
;                 d = MFMA32(ga, bw, d);
; #pragma unroll
;                 for (int r = 0; r < 16; ++r) d[r] = logsig_fast(d[r] + gbias) * 0.0625f;
;                 float sg[4], ps[4];
; #pragma unroll
;                 for (int g = 0; g < 4; ++g) { d[4 * g + 1] += d[4 * g]; d[4 * g + 2] += d[4 * g + 1]; d[4 * g + 3] += d[4 * g + 2]; sg[g] = d[4 * g + 3]; }
; #pragma unroll
;                 for (int g = 0; g < 4; ++g) ps[g] = __shfl_xor(sg[g], 32);
;                 float base_ = carry;
; #pragma unroll
;                 for (int g = 0; g < 4; ++g) { const float off = base_ + (hi ? ps[g] : 0.f);
; #pragma unroll
;                     for (int e = 0; e < 4; ++e) d[4 * g + e] += off;
;                     base_ += sg[g] + ps[g]; }
	v_cvt_pk_bf16_f32 v30, v12, v13
	s_waitcnt vmcnt(6)
	v_cvt_pk_bf16_f32 v31, v14, v15
	s_waitcnt vmcnt(4)
	v_cvt_pk_bf16_f32 v32, v16, v17
	s_waitcnt vmcnt(2)
	v_cvt_pk_bf16_f32 v33, v33, v52
	s_nop 1
	v_mfma_f32_32x32x16_bf16 v[2:17], v[2:5], v[30:33], 0
	s_waitcnt vmcnt(1)
	s_nop 10
	v_add_f32_e32 v2, v47, v2
	v_add_f32_e32 v3, v47, v3
	v_min_f32_e32 v50, 0, v2
	v_mul_f32_e64 v2, |v2|, s26
	v_mul_f32_e64 v51, |v3|, s26
	v_exp_f32_e32 v2, v2
	v_exp_f32_e32 v51, v51
	v_add_f32_e32 v4, v47, v4
	v_mul_f32_e64 v52, |v4|, s26
	v_add_f32_e32 v2, 1.0, v2
	v_add_f32_e32 v51, 1.0, v51
	v_cmp_gt_f32_e32 vcc, s44, v2
	v_cmp_gt_f32_e64 s[40:41], s44, v51
	v_exp_f32_e32 v52, v52
	v_cndmask_b32_e64 v53, 0, 32, vcc
	v_cndmask_b32_e64 v54, 0, 32, s[40:41]
	v_ldexp_f32 v2, v2, v53
	v_ldexp_f32 v51, v51, v54
	v_log_f32_e32 v2, v2
	v_log_f32_e32 v51, v51
	v_cndmask_b32_e32 v53, 0, v241, vcc
	v_add_f32_e32 v52, 1.0, v52
	v_mul_f32_e32 v55, 0x3f317217, v2
	v_mul_f32_e32 v56, 0x3f317217, v51
	v_fma_f32 v55, v2, s45, -v55
	v_fma_f32 v56, v51, s45, -v56
	v_fmac_f32_e32 v55, 0x3377d1cf, v2
	v_fmac_f32_e32 v56, 0x3377d1cf, v51
	v_fmac_f32_e32 v55, 0x3f317217, v2
	v_cmp_lt_f32_e64 vcc, |v2|, s47
	v_fmac_f32_e32 v56, 0x3f317217, v51
	v_add_f32_e32 v5, v47, v5
	v_cndmask_b32_e32 v2, v2, v55, vcc
	v_cmp_lt_f32_e64 vcc, |v51|, s47
	v_sub_f32_e32 v2, v2, v53
	v_sub_f32_e32 v2, v50, v2
	v_cndmask_b32_e32 v51, v51, v56, vcc
	v_cmp_gt_f32_e32 vcc, s44, v52
	v_cndmask_b32_e64 v54, 0, v241, s[40:41]
	v_min_f32_e32 v3, 0, v3
	v_cndmask_b32_e64 v50, 0, 32, vcc
	v_ldexp_f32 v50, v52, v50
	v_log_f32_e32 v50, v50
	v_mul_f32_e64 v52, |v5|, s26
	v_sub_f32_e32 v51, v51, v54
	v_exp_f32_e32 v52, v52
	v_sub_f32_e32 v3, v3, v51
	v_mul_f32_e32 v51, 0x3f317217, v50
	v_fma_f32 v51, v50, s45, -v51
	v_fmac_f32_e32 v51, 0x3377d1cf, v50
	v_fmac_f32_e32 v51, 0x3f317217, v50
	v_cmp_lt_f32_e64 s[40:41], |v50|, s47
	v_add_f32_e32 v52, 1.0, v52
	v_add_f32_e32 v6, v47, v6
	v_cndmask_b32_e64 v50, v50, v51, s[40:41]
	v_cndmask_b32_e32 v51, 0, v241, vcc
	v_cmp_gt_f32_e32 vcc, s44, v52
	v_sub_f32_e32 v50, v50, v51
	v_mul_f32_e64 v51, |v6|, s26
	v_cndmask_b32_e64 v53, 0, 32, vcc
	v_ldexp_f32 v52, v52, v53
	v_log_f32_e32 v52, v52
	v_min_f32_e32 v4, 0, v4
	v_exp_f32_e32 v51, v51
	v_sub_f32_e32 v4, v4, v50
	v_mul_f32_e32 v50, 0x3f317217, v52
	v_fma_f32 v50, v52, s45, -v50
	v_fmac_f32_e32 v50, 0x3377d1cf, v52
	v_fmac_f32_e32 v50, 0x3f317217, v52
	v_cmp_lt_f32_e64 s[40:41], |v52|, s47
	v_add_f32_e32 v51, 1.0, v51
	v_add_f32_e32 v7, v47, v7
	v_cndmask_b32_e64 v50, v52, v50, s[40:41]
	v_cndmask_b32_e32 v52, 0, v241, vcc
	v_cmp_gt_f32_e32 vcc, s44, v51
	v_sub_f32_e32 v50, v50, v52
	v_mul_f32_e64 v52, |v7|, s26
	v_cndmask_b32_e64 v53, 0, 32, vcc
	v_ldexp_f32 v51, v51, v53
	v_log_f32_e32 v51, v51
	v_min_f32_e32 v5, 0, v5
	v_exp_f32_e32 v52, v52
	v_sub_f32_e32 v5, v5, v50
	v_mul_f32_e32 v50, 0x3f317217, v51
	v_fma_f32 v50, v51, s45, -v50
	v_fmac_f32_e32 v50, 0x3377d1cf, v51
	v_fmac_f32_e32 v50, 0x3f317217, v51
	v_cmp_lt_f32_e64 s[40:41], |v51|, s47
	v_add_f32_e32 v52, 1.0, v52
	v_add_f32_e32 v8, v47, v8
	v_cndmask_b32_e64 v50, v51, v50, s[40:41]
	v_cndmask_b32_e32 v51, 0, v241, vcc
	v_cmp_gt_f32_e32 vcc, s44, v52
	v_sub_f32_e32 v50, v50, v51
	v_mul_f32_e64 v51, |v8|, s26
	v_cndmask_b32_e64 v53, 0, 32, vcc
	v_ldexp_f32 v52, v52, v53
	v_log_f32_e32 v52, v52
	v_min_f32_e32 v6, 0, v6
	v_exp_f32_e32 v51, v51
	v_sub_f32_e32 v6, v6, v50
	v_mul_f32_e32 v50, 0x3f317217, v52
	v_fma_f32 v50, v52, s45, -v50
	v_fmac_f32_e32 v50, 0x3377d1cf, v52
	v_fmac_f32_e32 v50, 0x3f317217, v52
	v_cmp_lt_f32_e64 s[40:41], |v52|, s47
	v_add_f32_e32 v51, 1.0, v51
	v_add_f32_e32 v9, v47, v9
	v_cndmask_b32_e64 v50, v52, v50, s[40:41]
	v_cndmask_b32_e32 v52, 0, v241, vcc
	v_cmp_gt_f32_e32 vcc, s44, v51
	v_sub_f32_e32 v50, v50, v52
	v_min_f32_e32 v7, 0, v7
	v_cndmask_b32_e64 v52, 0, 32, vcc
	v_ldexp_f32 v51, v51, v52
	v_log_f32_e32 v51, v51
	v_mul_f32_e64 v52, |v9|, s26
	v_exp_f32_e32 v52, v52
	v_sub_f32_e32 v7, v7, v50
	v_mul_f32_e32 v50, 0x3f317217, v51
	v_fma_f32 v50, v51, s45, -v50
	v_fmac_f32_e32 v50, 0x3377d1cf, v51
	v_fmac_f32_e32 v50, 0x3f317217, v51
	v_cmp_lt_f32_e64 s[40:41], |v51|, s47
	v_add_f32_e32 v52, 1.0, v52
	v_add_f32_e32 v10, v47, v10
	v_cndmask_b32_e64 v50, v51, v50, s[40:41]
	v_cndmask_b32_e32 v51, 0, v241, vcc
	v_cmp_gt_f32_e32 vcc, s44, v52
	v_sub_f32_e32 v50, v50, v51
	v_mul_f32_e64 v51, |v10|, s26
	v_cndmask_b32_e64 v53, 0, 32, vcc
	v_ldexp_f32 v52, v52, v53
	v_log_f32_e32 v52, v52
	v_min_f32_e32 v8, 0, v8
	v_exp_f32_e32 v51, v51
	v_sub_f32_e32 v8, v8, v50
	v_mul_f32_e32 v50, 0x3f317217, v52
	v_fma_f32 v50, v52, s45, -v50
	v_fmac_f32_e32 v50, 0x3377d1cf, v52
	v_fmac_f32_e32 v50, 0x3f317217, v52
	v_cmp_lt_f32_e64 s[40:41], |v52|, s47
	v_add_f32_e32 v51, 1.0, v51
	v_add_f32_e32 v11, v47, v11
	v_cndmask_b32_e64 v50, v52, v50, s[40:41]
	v_cndmask_b32_e32 v52, 0, v241, vcc
	v_cmp_gt_f32_e32 vcc, s44, v51
	v_sub_f32_e32 v50, v50, v52
	v_mul_f32_e64 v52, |v11|, s26
	v_cndmask_b32_e64 v53, 0, 32, vcc
	v_ldexp_f32 v51, v51, v53
	v_log_f32_e32 v51, v51
	v_min_f32_e32 v9, 0, v9
	v_exp_f32_e32 v52, v52
	v_sub_f32_e32 v9, v9, v50
	v_mul_f32_e32 v50, 0x3f317217, v51
	v_fma_f32 v50, v51, s45, -v50
	v_fmac_f32_e32 v50, 0x3377d1cf, v51
	v_fmac_f32_e32 v50, 0x3f317217, v51
	v_cmp_lt_f32_e64 s[40:41], |v51|, s47
	v_add_f32_e32 v52, 1.0, v52
	v_add_f32_e32 v12, v47, v12
	v_cndmask_b32_e64 v50, v51, v50, s[40:41]
	v_cndmask_b32_e32 v51, 0, v241, vcc
	v_cmp_gt_f32_e32 vcc, s44, v52
	v_sub_f32_e32 v50, v50, v51
	v_mul_f32_e64 v51, |v12|, s26
	v_cndmask_b32_e64 v53, 0, 32, vcc
	v_ldexp_f32 v52, v52, v53
	v_log_f32_e32 v52, v52
	v_min_f32_e32 v10, 0, v10
; DI float logsig_fast(float x) { return fminf(x, 0.f) - __logf(1.f + __expf(-fabsf(x))); }
; template <int PH>
; DI void gla_unit(LAS char* lds, int unit, const bf16* PROJ, const float* W2, const float* gb, bf16* SC, float* DEC, const float* cnorm, bf16* MIXED, bf16* QG, bf16* KG) {
;     ...
;                 for (int r = 0; r < 16; ++r) d[r] = logsig_fast(d[r] + gbias) * 0.0625f;
;                 float sg[4], ps[4];
; #pragma unroll
;                 for (int g = 0; g < 4; ++g) { d[4 * g + 1] += d[4 * g]; d[4 * g + 2] += d[4 * g + 1]; d[4 * g + 3] += d[4 * g + 2]; sg[g] = d[4 * g + 3]; }
; #pragma unroll
;                 for (int g = 0; g < 4; ++g) ps[g] = __shfl_xor(sg[g], 32);
;                 float base_ = carry;
; #pragma unroll
;                 for (int g = 0; g < 4; ++g) { const float off = base_ + (hi ? ps[g] : 0.f);
; #pragma unroll
;                     for (int e = 0; e < 4; ++e) d[4 * g + e] += off;
;                     base_ += sg[g] + ps[g]; }
;                 carry = base_;
	v_exp_f32_e32 v51, v51
	v_sub_f32_e32 v10, v10, v50
	v_mul_f32_e32 v50, 0x3f317217, v52
	v_fma_f32 v50, v52, s45, -v50
	v_fmac_f32_e32 v50, 0x3377d1cf, v52
	v_fmac_f32_e32 v50, 0x3f317217, v52
	v_cmp_lt_f32_e64 s[40:41], |v52|, s47
	v_add_f32_e32 v51, 1.0, v51
	v_add_f32_e32 v13, v47, v13
	v_cndmask_b32_e64 v50, v52, v50, s[40:41]
	v_cndmask_b32_e32 v52, 0, v241, vcc
	v_cmp_gt_f32_e32 vcc, s44, v51
	v_sub_f32_e32 v50, v50, v52
	v_min_f32_e32 v11, 0, v11
	v_cndmask_b32_e64 v52, 0, 32, vcc
	v_ldexp_f32 v51, v51, v52
	v_log_f32_e32 v51, v51
	v_mul_f32_e64 v52, |v13|, s26
	v_exp_f32_e32 v52, v52
	v_sub_f32_e32 v11, v11, v50
	v_mul_f32_e32 v50, 0x3f317217, v51
	v_fma_f32 v50, v51, s45, -v50
	v_fmac_f32_e32 v50, 0x3377d1cf, v51
	v_fmac_f32_e32 v50, 0x3f317217, v51
	v_cmp_lt_f32_e64 s[40:41], |v51|, s47
	v_add_f32_e32 v52, 1.0, v52
	v_add_f32_e32 v14, v47, v14
	v_cndmask_b32_e64 v50, v51, v50, s[40:41]
	v_cndmask_b32_e32 v51, 0, v241, vcc
	v_cmp_gt_f32_e32 vcc, s44, v52
	v_sub_f32_e32 v50, v50, v51
	v_mul_f32_e64 v51, |v14|, s26
	v_cndmask_b32_e64 v53, 0, 32, vcc
	v_ldexp_f32 v52, v52, v53
	v_log_f32_e32 v52, v52
	v_min_f32_e32 v12, 0, v12
	v_exp_f32_e32 v51, v51
	v_sub_f32_e32 v12, v12, v50
	v_mul_f32_e32 v50, 0x3f317217, v52
	v_fma_f32 v50, v52, s45, -v50
	v_fmac_f32_e32 v50, 0x3377d1cf, v52
	v_fmac_f32_e32 v50, 0x3f317217, v52
	v_cmp_lt_f32_e64 s[40:41], |v52|, s47
	v_add_f32_e32 v51, 1.0, v51
	v_add_f32_e32 v15, v47, v15
	v_cndmask_b32_e64 v50, v52, v50, s[40:41]
	v_cndmask_b32_e32 v52, 0, v241, vcc
	v_cmp_gt_f32_e32 vcc, s44, v51
	v_sub_f32_e32 v50, v50, v52
	v_mul_f32_e64 v52, |v15|, s26
	v_cndmask_b32_e64 v53, 0, 32, vcc
	v_ldexp_f32 v51, v51, v53
	v_log_f32_e32 v51, v51
	v_min_f32_e32 v13, 0, v13
	v_exp_f32_e32 v52, v52
	v_sub_f32_e32 v13, v13, v50
	v_mul_f32_e32 v50, 0x3f317217, v51
	v_fma_f32 v50, v51, s45, -v50
	v_fmac_f32_e32 v50, 0x3377d1cf, v51
	v_fmac_f32_e32 v50, 0x3f317217, v51
	v_cmp_lt_f32_e64 s[40:41], |v51|, s47
	v_add_f32_e32 v52, 1.0, v52
	v_add_f32_e32 v16, v47, v16
	v_cndmask_b32_e64 v50, v51, v50, s[40:41]
	v_cndmask_b32_e32 v51, 0, v241, vcc
	v_cmp_gt_f32_e32 vcc, s44, v52
	v_sub_f32_e32 v50, v50, v51
	v_mul_f32_e64 v51, |v16|, s26
	v_cndmask_b32_e64 v53, 0, 32, vcc
	v_ldexp_f32 v52, v52, v53
	v_log_f32_e32 v52, v52
	v_min_f32_e32 v14, 0, v14
	v_exp_f32_e32 v51, v51
	v_sub_f32_e32 v14, v14, v50
	v_mul_f32_e32 v50, 0x3f317217, v52
	v_fma_f32 v50, v52, s45, -v50
	v_fmac_f32_e32 v50, 0x3377d1cf, v52
	v_fmac_f32_e32 v50, 0x3f317217, v52
	v_cmp_lt_f32_e64 s[40:41], |v52|, s47
	v_add_f32_e32 v51, 1.0, v51
	v_add_f32_e32 v17, v47, v17
	v_cndmask_b32_e64 v50, v52, v50, s[40:41]
	v_cndmask_b32_e32 v52, 0, v241, vcc
	v_cmp_gt_f32_e32 vcc, s44, v51
	v_sub_f32_e32 v50, v50, v52
	v_min_f32_e32 v15, 0, v15
	v_cndmask_b32_e64 v52, 0, 32, vcc
	v_ldexp_f32 v51, v51, v52
	v_log_f32_e32 v51, v51
	v_mul_f32_e64 v52, |v17|, s26
	v_exp_f32_e32 v52, v52
	v_sub_f32_e32 v15, v15, v50
	v_mul_f32_e32 v50, 0x3f317217, v51
	v_fma_f32 v50, v51, s45, -v50
	v_fmac_f32_e32 v50, 0x3377d1cf, v51
	v_fmac_f32_e32 v50, 0x3f317217, v51
	v_cmp_lt_f32_e64 s[40:41], |v51|, s47
	v_add_f32_e32 v52, 1.0, v52
	v_min_f32_e32 v16, 0, v16
	v_cndmask_b32_e64 v50, v51, v50, s[40:41]
	v_cndmask_b32_e32 v51, 0, v241, vcc
	v_cmp_gt_f32_e32 vcc, s44, v52
	v_sub_f32_e32 v50, v50, v51
	v_sub_f32_e32 v16, v16, v50
	v_cndmask_b32_e64 v53, 0, 32, vcc
	v_ldexp_f32 v52, v52, v53
	v_log_f32_e32 v52, v52
	v_mul_f32_e32 v3, 0x3d800000, v3
	v_fmac_f32_e32 v3, 0x3d800000, v2
	v_cndmask_b32_e32 v51, 0, v241, vcc
	v_mul_f32_e32 v50, 0x3f317217, v52
	v_fma_f32 v50, v52, s45, -v50
	v_fmac_f32_e32 v50, 0x3377d1cf, v52
	v_fmac_f32_e32 v50, 0x3f317217, v52
	v_cmp_lt_f32_e64 s[40:41], |v52|, s47
	v_fmamk_f32 v4, v4, 0x3d800000, v3
	v_mul_f32_e32 v7, 0x3d800000, v7
	v_cndmask_b32_e64 v50, v52, v50, s[40:41]
	v_min_f32_e32 v17, 0, v17
	v_sub_f32_e32 v50, v50, v51
	v_fmamk_f32 v5, v5, 0x3d800000, v4
	v_sub_f32_e32 v17, v17, v50
	v_fmac_f32_e32 v7, 0x3d800000, v6
	ds_bpermute_b32 v50, v48, v5
	v_fmamk_f32 v8, v8, 0x3d800000, v7
	v_mul_f32_e32 v11, 0x3d800000, v11
	v_fmamk_f32 v9, v9, 0x3d800000, v8
	v_fmac_f32_e32 v11, 0x3d800000, v10
	ds_bpermute_b32 v51, v48, v9
	v_fmamk_f32 v12, v12, 0x3d800000, v11
	v_mul_f32_e32 v15, 0x3d800000, v15
	v_fmamk_f32 v13, v13, 0x3d800000, v12
	s_waitcnt lgkmcnt(1)
	v_add_f32_e32 v54, 0, v50
	v_cmp_gt_u32_e32 vcc, 32, v45
	v_fmac_f32_e32 v15, 0x3d800000, v14
	ds_bpermute_b32 v52, v48, v13
	v_cndmask_b32_e64 v54, v54, 0, vcc
	v_fmamk_f32 v16, v16, 0x3d800000, v15
	v_fmamk_f32 v2, v2, 0x3d800000, v54
	v_add_f32_e32 v3, v54, v3
	v_add_f32_e32 v4, v54, v4
	v_add_f32_e32 v54, v54, v5
	v_add_f32_e32 v5, v5, v50
	v_fmamk_f32 v17, v17, 0x3d800000, v16
	v_add_f32_e32 v5, 0, v5
	s_waitcnt lgkmcnt(1)
	v_cndmask_b32_e64 v50, v51, 0, vcc
	ds_bpermute_b32 v53, v48, v17
	v_add_f32_e32 v50, v50, v5
	v_fmamk_f32 v6, v6, 0x3d800000, v50
	v_add_f32_e32 v7, v7, v50
	v_add_f32_e32 v8, v8, v50
	v_add_f32_e32 v50, v9, v50
	v_add_f32_e32 v9, v9, v51
	v_add_f32_e32 v5, v9, v5
	s_waitcnt lgkmcnt(1)
	v_cndmask_b32_e64 v9, v52, 0, vcc
	v_add_f32_e32 v9, v9, v5
	v_fmamk_f32 v10, v10, 0x3d800000, v9
	v_add_f32_e32 v11, v11, v9
	v_add_f32_e32 v12, v12, v9
	v_add_f32_e32 v9, v13, v9
	v_add_f32_e32 v13, v13, v52
	v_add_f32_e32 v51, v13, v5
	s_waitcnt lgkmcnt(0)
; DI int crow(int r, int hi) { return (r & 3) + 8 * (r >> 2) + 4 * hi; }
; #define MFMA32(a, b, c) __builtin_amdgcn_mfma_f32_32x32x16_bf16((a), (b), (c), 0, 0, 0)
; DI float logsig_fast(float x) { return fminf(x, 0.f) - __logf(1.f + __expf(-fabsf(x))); }
; __device__ __forceinline__ int crow(int r,int hi){return (r&3)+8*(r>>2)+4*hi;}
; template <int PH>
; DI void gla_unit(LAS char* lds, int unit, const bf16* PROJ, const float* W2, const float* gb, bf16* SC, float* DEC, const float* cnorm, bf16* MIXED, bf16* QG, bf16* KG) {
;     ...
;             for (int mi = 0; mi < 2; ++mi) {
;                 const bf16x8 ga = *(const bf16x8*)(PROJ + (row0 + 32 * mi + r32) * PROJP + O_GL + 8 * hi);
;                 f32x16 d;
; #pragma unroll
;                 for (int r = 0; r < 16; ++r) d[r] = 0.f;
;                 d = MFMA32(ga, bw, d);
; #pragma unroll
;                 for (int r = 0; r < 16; ++r) d[r] = logsig_fast(d[r] + gbias) * 0.0625f;
;                 float sg[4], ps[4];
; #pragma unroll
;                 for (int g = 0; g < 4; ++g) { d[4 * g + 1] += d[4 * g]; d[4 * g + 2] += d[4 * g + 1]; d[4 * g + 3] += d[4 * g + 2]; sg[g] = d[4 * g + 3]; }
; #pragma unroll
;                 for (int g = 0; g < 4; ++g) ps[g] = __shfl_xor(sg[g], 32);
;                 float base_ = carry;
; #pragma unroll
;                 for (int g = 0; g < 4; ++g) { const float off = base_ + (hi ? ps[g] : 0.f);
; #pragma unroll
;                     for (int e = 0; e < 4; ++e) d[4 * g + e] += off;
;                     base_ += sg[g] + ps[g]; }
;                 carry = base_;
; #pragma unroll
;                 for (int r = 0; r < 16; ++r) BL[(32 * mi + crow(r, hi)) * 96 + k] = d[r];
	v_cndmask_b32_e64 v5, v53, 0, vcc
	v_add_f32_e32 v5, v5, v51
	v_fmamk_f32 v52, v14, 0x3d800000, v5
	v_add_f32_e32 v55, v15, v5
	v_add_f32_e32 v56, v16, v5
	v_add_f32_e32 v57, v17, v5
	v_mul_u32_u24_e32 v5, 0x600, v41
	v_add3_u32 v49, 0, v49, v5
	ds_write2_b32 v49, v2, v3 offset1:96
	v_add_u32_e32 v2, 0x200, v49
	ds_write2_b32 v2, v4, v54 offset0:64 offset1:160
	v_add_u32_e32 v2, 0xc00, v49
	ds_write2_b32 v2, v6, v7 offset1:96
	v_add_u32_e32 v2, 0xe00, v49
	ds_write2_b32 v2, v8, v50 offset0:64 offset1:160
	v_add_u32_e32 v2, 0x1800, v49
	ds_write2_b32 v2, v10, v11 offset1:96
	v_add_u32_e32 v2, 0x1a00, v49
	v_add_f32_e32 v53, v17, v53
	ds_write2_b32 v2, v12, v9 offset0:64 offset1:160
	s_waitcnt vmcnt(0)
	v_mfma_f32_32x32x16_bf16 v[2:17], v[26:29], v[30:33], 0
	v_add_u32_e32 v27, 0x2400, v49
	ds_write2_b32 v27, v52, v55 offset1:96
	v_add_u32_e32 v27, 0x2600, v49
	ds_write2_b32 v27, v56, v57 offset0:64 offset1:160
	v_add_f32_e32 v27, v53, v51
	s_nop 6
	v_add_f32_e32 v2, v47, v2
	v_mul_f32_e64 v26, |v2|, s26
	v_exp_f32_e32 v26, v26
	v_add_f32_e32 v3, v47, v3
	v_mul_f32_e64 v29, |v3|, s26
	v_exp_f32_e32 v29, v29
	v_add_f32_e32 v26, 1.0, v26
	v_cmp_gt_f32_e64 s[40:41], s44, v26
	v_add_f32_e32 v4, v47, v4
	v_add_f32_e32 v29, 1.0, v29
	v_cndmask_b32_e64 v28, 0, 32, s[40:41]
	v_ldexp_f32 v26, v26, v28
	v_log_f32_e32 v26, v26
	v_min_f32_e32 v2, 0, v2
	v_add_f32_e32 v5, v47, v5
	v_min_f32_e32 v3, 0, v3
	v_mul_f32_e32 v28, 0x3f317217, v26
	v_fma_f32 v28, v26, s45, -v28
	v_fmac_f32_e32 v28, 0x3377d1cf, v26
	v_fmac_f32_e32 v28, 0x3f317217, v26
	v_cmp_lt_f32_e64 s[42:43], |v26|, s47
	v_add_f32_e32 v6, v47, v6
	v_add_f32_e32 v7, v47, v7
	v_cndmask_b32_e64 v26, v26, v28, s[42:43]
	v_cndmask_b32_e64 v28, 0, v241, s[40:41]
	v_cmp_gt_f32_e64 s[40:41], s44, v29
	v_sub_f32_e32 v26, v26, v28
	v_mul_f32_e64 v28, |v4|, s26
	v_cndmask_b32_e64 v30, 0, 32, s[40:41]
	v_ldexp_f32 v29, v29, v30
	v_log_f32_e32 v29, v29
	v_exp_f32_e32 v28, v28
	v_sub_f32_e32 v2, v2, v26
	v_min_f32_e32 v4, 0, v4
	v_mul_f32_e32 v26, 0x3f317217, v29
	v_fma_f32 v26, v29, s45, -v26
	v_fmac_f32_e32 v26, 0x3377d1cf, v29
	v_fmac_f32_e32 v26, 0x3f317217, v29
	v_cmp_lt_f32_e64 s[42:43], |v29|, s47
	v_add_f32_e32 v28, 1.0, v28
	v_add_f32_e32 v8, v47, v8
	v_cndmask_b32_e64 v26, v29, v26, s[42:43]
	v_cndmask_b32_e64 v29, 0, v241, s[40:41]
	v_cmp_gt_f32_e64 s[40:41], s44, v28
	v_sub_f32_e32 v26, v26, v29
	v_sub_f32_e32 v3, v3, v26
	v_cndmask_b32_e64 v29, 0, 32, s[40:41]
	v_ldexp_f32 v28, v28, v29
	v_log_f32_e32 v28, v28
	v_mul_f32_e64 v29, |v5|, s26
	v_exp_f32_e32 v29, v29
	v_min_f32_e32 v5, 0, v5
	v_mul_f32_e32 v26, 0x3f317217, v28
	v_fma_f32 v26, v28, s45, -v26
	v_fmac_f32_e32 v26, 0x3377d1cf, v28
	v_fmac_f32_e32 v26, 0x3f317217, v28
	v_cmp_lt_f32_e64 s[42:43], |v28|, s47
	v_add_f32_e32 v29, 1.0, v29
	v_add_f32_e32 v9, v47, v9
	v_cndmask_b32_e64 v26, v28, v26, s[42:43]
	v_cndmask_b32_e64 v28, 0, v241, s[40:41]
	v_cmp_gt_f32_e64 s[40:41], s44, v29
	v_sub_f32_e32 v26, v26, v28
	v_mul_f32_e64 v28, |v6|, s26
	v_cndmask_b32_e64 v30, 0, 32, s[40:41]
	v_ldexp_f32 v29, v29, v30
	v_log_f32_e32 v29, v29
	v_exp_f32_e32 v28, v28
	v_sub_f32_e32 v4, v4, v26
	v_min_f32_e32 v6, 0, v6
	v_mul_f32_e32 v26, 0x3f317217, v29
	v_fma_f32 v26, v29, s45, -v26
	v_fmac_f32_e32 v26, 0x3377d1cf, v29
	v_fmac_f32_e32 v26, 0x3f317217, v29
	v_cmp_lt_f32_e64 s[42:43], |v29|, s47
	v_add_f32_e32 v28, 1.0, v28
	v_add_f32_e32 v10, v47, v10
	v_cndmask_b32_e64 v26, v29, v26, s[42:43]
	v_cndmask_b32_e64 v29, 0, v241, s[40:41]
	v_cmp_gt_f32_e64 s[40:41], s44, v28
	v_sub_f32_e32 v26, v26, v29
	v_mul_f32_e64 v29, |v7|, s26
	v_cndmask_b32_e64 v30, 0, 32, s[40:41]
	v_ldexp_f32 v28, v28, v30
	v_log_f32_e32 v28, v28
	v_exp_f32_e32 v29, v29
	v_sub_f32_e32 v5, v5, v26
	v_min_f32_e32 v7, 0, v7
	v_mul_f32_e32 v26, 0x3f317217, v28
	v_fma_f32 v26, v28, s45, -v26
	v_fmac_f32_e32 v26, 0x3377d1cf, v28
	v_fmac_f32_e32 v26, 0x3f317217, v28
	v_cmp_lt_f32_e64 s[42:43], |v28|, s47
	v_add_f32_e32 v29, 1.0, v29
	v_add_f32_e32 v11, v47, v11
	v_cndmask_b32_e64 v26, v28, v26, s[42:43]
	v_cndmask_b32_e64 v28, 0, v241, s[40:41]
	v_cmp_gt_f32_e64 s[40:41], s44, v29
	v_sub_f32_e32 v26, v26, v28
	v_mul_f32_e64 v28, |v8|, s26
	v_cndmask_b32_e64 v30, 0, 32, s[40:41]
	v_ldexp_f32 v29, v29, v30
	v_log_f32_e32 v29, v29
	v_exp_f32_e32 v28, v28
	v_sub_f32_e32 v6, v6, v26
	v_min_f32_e32 v8, 0, v8
	v_mul_f32_e32 v26, 0x3f317217, v29
	v_fma_f32 v26, v29, s45, -v26
	v_fmac_f32_e32 v26, 0x3377d1cf, v29
	v_fmac_f32_e32 v26, 0x3f317217, v29
	v_cmp_lt_f32_e64 s[42:43], |v29|, s47
	v_add_f32_e32 v28, 1.0, v28
	v_add_f32_e32 v12, v47, v12
	v_cndmask_b32_e64 v26, v29, v26, s[42:43]
	v_cndmask_b32_e64 v29, 0, v241, s[40:41]
	v_cmp_gt_f32_e64 s[40:41], s44, v28
	v_sub_f32_e32 v26, v26, v29
	v_sub_f32_e32 v7, v7, v26
	v_cndmask_b32_e64 v29, 0, 32, s[40:41]
	v_ldexp_f32 v28, v28, v29
	v_log_f32_e32 v28, v28
	v_mul_f32_e64 v29, |v9|, s26
	v_exp_f32_e32 v29, v29
	v_min_f32_e32 v9, 0, v9
	v_mul_f32_e32 v26, 0x3f317217, v28
	v_fma_f32 v26, v28, s45, -v26
	v_fmac_f32_e32 v26, 0x3377d1cf, v28
	v_fmac_f32_e32 v26, 0x3f317217, v28
	v_cmp_lt_f32_e64 s[42:43], |v28|, s47
	v_add_f32_e32 v29, 1.0, v29
	v_add_f32_e32 v13, v47, v13
	v_cndmask_b32_e64 v26, v28, v26, s[42:43]
	v_cndmask_b32_e64 v28, 0, v241, s[40:41]
	v_cmp_gt_f32_e64 s[40:41], s44, v29
	v_sub_f32_e32 v26, v26, v28
	v_mul_f32_e64 v28, |v10|, s26
	v_cndmask_b32_e64 v30, 0, 32, s[40:41]
	v_ldexp_f32 v29, v29, v30
	v_log_f32_e32 v29, v29
	v_exp_f32_e32 v28, v28
	v_sub_f32_e32 v8, v8, v26
	v_min_f32_e32 v10, 0, v10
	v_mul_f32_e32 v26, 0x3f317217, v29
	v_fma_f32 v26, v29, s45, -v26
	v_fmac_f32_e32 v26, 0x3377d1cf, v29
	v_fmac_f32_e32 v26, 0x3f317217, v29
; DI int crow(int r, int hi) { return (r & 3) + 8 * (r >> 2) + 4 * hi; }
; DI float logsig_fast(float x) { return fminf(x, 0.f) - __logf(1.f + __expf(-fabsf(x))); }
; __device__ __forceinline__ int crow(int r,int hi){return (r&3)+8*(r>>2)+4*hi;}
; template <int PH>
; DI void gla_unit(LAS char* lds, int unit, const bf16* PROJ, const float* W2, const float* gb, bf16* SC, float* DEC, const float* cnorm, bf16* MIXED, bf16* QG, bf16* KG) {
;     ...
;                 for (int r = 0; r < 16; ++r) d[r] = logsig_fast(d[r] + gbias) * 0.0625f;
;                 float sg[4], ps[4];
; #pragma unroll
;                 for (int g = 0; g < 4; ++g) { d[4 * g + 1] += d[4 * g]; d[4 * g + 2] += d[4 * g + 1]; d[4 * g + 3] += d[4 * g + 2]; sg[g] = d[4 * g + 3]; }
; #pragma unroll
;                 for (int g = 0; g < 4; ++g) ps[g] = __shfl_xor(sg[g], 32);
;                 float base_ = carry;
; #pragma unroll
;                 for (int g = 0; g < 4; ++g) { const float off = base_ + (hi ? ps[g] : 0.f);
; #pragma unroll
;                     for (int e = 0; e < 4; ++e) d[4 * g + e] += off;
;                     base_ += sg[g] + ps[g]; }
;                 carry = base_;
; #pragma unroll
;                 for (int r = 0; r < 16; ++r) BL[(32 * mi + crow(r, hi)) * 96 + k] = d[r];
	v_cmp_lt_f32_e64 s[42:43], |v29|, s47
	v_add_f32_e32 v28, 1.0, v28
	v_add_f32_e32 v14, v47, v14
	v_cndmask_b32_e64 v26, v29, v26, s[42:43]
	v_cndmask_b32_e64 v29, 0, v241, s[40:41]
	v_cmp_gt_f32_e64 s[40:41], s44, v28
	v_sub_f32_e32 v26, v26, v29
	v_mul_f32_e64 v29, |v11|, s26
	v_cndmask_b32_e64 v30, 0, 32, s[40:41]
	v_ldexp_f32 v28, v28, v30
	v_log_f32_e32 v28, v28
	v_exp_f32_e32 v29, v29
	v_sub_f32_e32 v9, v9, v26
	v_min_f32_e32 v11, 0, v11
	v_mul_f32_e32 v26, 0x3f317217, v28
	v_fma_f32 v26, v28, s45, -v26
	v_fmac_f32_e32 v26, 0x3377d1cf, v28
	v_fmac_f32_e32 v26, 0x3f317217, v28
	v_cmp_lt_f32_e64 s[42:43], |v28|, s47
	v_add_f32_e32 v29, 1.0, v29
	v_add_f32_e32 v15, v47, v15
	v_cndmask_b32_e64 v26, v28, v26, s[42:43]
	v_cndmask_b32_e64 v28, 0, v241, s[40:41]
	v_cmp_gt_f32_e64 s[40:41], s44, v29
	v_sub_f32_e32 v26, v26, v28
	v_mul_f32_e64 v28, |v12|, s26
	v_cndmask_b32_e64 v30, 0, 32, s[40:41]
	v_ldexp_f32 v29, v29, v30
	v_log_f32_e32 v29, v29
	v_exp_f32_e32 v28, v28
	v_sub_f32_e32 v10, v10, v26
	v_min_f32_e32 v12, 0, v12
	v_mul_f32_e32 v26, 0x3f317217, v29
	v_fma_f32 v26, v29, s45, -v26
	v_fmac_f32_e32 v26, 0x3377d1cf, v29
	v_fmac_f32_e32 v26, 0x3f317217, v29
	v_cmp_lt_f32_e64 s[42:43], |v29|, s47
	v_add_f32_e32 v28, 1.0, v28
	v_add_f32_e32 v16, v47, v16
	v_cndmask_b32_e64 v26, v29, v26, s[42:43]
	v_cndmask_b32_e64 v29, 0, v241, s[40:41]
	v_cmp_gt_f32_e64 s[40:41], s44, v28
	v_sub_f32_e32 v26, v26, v29
	v_sub_f32_e32 v11, v11, v26
	v_cndmask_b32_e64 v29, 0, 32, s[40:41]
	v_ldexp_f32 v28, v28, v29
	v_log_f32_e32 v28, v28
	v_mul_f32_e64 v29, |v13|, s26
	v_exp_f32_e32 v29, v29
	v_min_f32_e32 v13, 0, v13
	v_mul_f32_e32 v26, 0x3f317217, v28
	v_fma_f32 v26, v28, s45, -v26
	v_fmac_f32_e32 v26, 0x3377d1cf, v28
	v_fmac_f32_e32 v26, 0x3f317217, v28
	v_cmp_lt_f32_e64 s[42:43], |v28|, s47
	v_add_f32_e32 v29, 1.0, v29
	v_add_f32_e32 v17, v47, v17
	v_cndmask_b32_e64 v26, v28, v26, s[42:43]
	v_cndmask_b32_e64 v28, 0, v241, s[40:41]
	v_cmp_gt_f32_e64 s[40:41], s44, v29
	v_sub_f32_e32 v26, v26, v28
	v_mul_f32_e64 v28, |v14|, s26
	v_cndmask_b32_e64 v30, 0, 32, s[40:41]
	v_ldexp_f32 v29, v29, v30
	v_log_f32_e32 v29, v29
	v_exp_f32_e32 v28, v28
	v_sub_f32_e32 v12, v12, v26
	v_min_f32_e32 v14, 0, v14
	v_mul_f32_e32 v26, 0x3f317217, v29
	v_fma_f32 v26, v29, s45, -v26
	v_fmac_f32_e32 v26, 0x3377d1cf, v29
	v_fmac_f32_e32 v26, 0x3f317217, v29
	v_cmp_lt_f32_e64 s[42:43], |v29|, s47
	v_add_f32_e32 v28, 1.0, v28
	v_mul_f32_e32 v3, 0x3d800000, v3
	v_cndmask_b32_e64 v26, v29, v26, s[42:43]
	v_cndmask_b32_e64 v29, 0, v241, s[40:41]
	v_cmp_gt_f32_e64 s[40:41], s44, v28
	v_sub_f32_e32 v26, v26, v29
	v_mul_f32_e64 v29, |v15|, s26
	v_cndmask_b32_e64 v30, 0, 32, s[40:41]
	v_ldexp_f32 v28, v28, v30
	v_log_f32_e32 v28, v28
	v_exp_f32_e32 v29, v29
	v_sub_f32_e32 v13, v13, v26
	v_min_f32_e32 v15, 0, v15
	v_mul_f32_e32 v26, 0x3f317217, v28
	v_fma_f32 v26, v28, s45, -v26
	v_fmac_f32_e32 v26, 0x3377d1cf, v28
	v_fmac_f32_e32 v26, 0x3f317217, v28
	v_cmp_lt_f32_e64 s[42:43], |v28|, s47
	v_add_f32_e32 v29, 1.0, v29
	v_fmac_f32_e32 v3, 0x3d800000, v2
	v_cndmask_b32_e64 v26, v28, v26, s[42:43]
	v_cndmask_b32_e64 v28, 0, v241, s[40:41]
	v_cmp_gt_f32_e64 s[40:41], s44, v29
	v_sub_f32_e32 v26, v26, v28
	v_mul_f32_e64 v28, |v16|, s26
	v_cndmask_b32_e64 v30, 0, 32, s[40:41]
	v_ldexp_f32 v29, v29, v30
	v_log_f32_e32 v29, v29
	v_exp_f32_e32 v28, v28
	v_sub_f32_e32 v14, v14, v26
	v_min_f32_e32 v16, 0, v16
	v_mul_f32_e32 v26, 0x3f317217, v29
	v_fma_f32 v26, v29, s45, -v26
	v_fmac_f32_e32 v26, 0x3377d1cf, v29
	v_fmac_f32_e32 v26, 0x3f317217, v29
	v_cmp_lt_f32_e64 s[42:43], |v29|, s47
	v_add_f32_e32 v28, 1.0, v28
	v_fmamk_f32 v4, v4, 0x3d800000, v3
	v_cndmask_b32_e64 v26, v29, v26, s[42:43]
	v_cndmask_b32_e64 v29, 0, v241, s[40:41]
	v_cmp_gt_f32_e64 s[40:41], s44, v28
	v_sub_f32_e32 v26, v26, v29
	v_sub_f32_e32 v15, v15, v26
	v_cndmask_b32_e64 v29, 0, 32, s[40:41]
	v_ldexp_f32 v28, v28, v29
	v_log_f32_e32 v28, v28
	v_mul_f32_e64 v29, |v17|, s26
	v_exp_f32_e32 v29, v29
	v_mul_f32_e32 v7, 0x3d800000, v7
	v_mul_f32_e32 v26, 0x3f317217, v28
	v_fma_f32 v26, v28, s45, -v26
	v_fmac_f32_e32 v26, 0x3377d1cf, v28
	v_fmac_f32_e32 v26, 0x3f317217, v28
	v_cmp_lt_f32_e64 s[42:43], |v28|, s47
	v_add_f32_e32 v29, 1.0, v29
	v_min_f32_e32 v17, 0, v17
	v_cndmask_b32_e64 v26, v28, v26, s[42:43]
	v_cndmask_b32_e64 v28, 0, v241, s[40:41]
	v_cmp_gt_f32_e64 s[40:41], s44, v29
	v_sub_f32_e32 v26, v26, v28
	v_sub_f32_e32 v16, v16, v26
	v_cndmask_b32_e64 v30, 0, 32, s[40:41]
	v_ldexp_f32 v29, v29, v30
	v_log_f32_e32 v29, v29
	v_cndmask_b32_e64 v28, 0, v241, s[40:41]
	v_fmamk_f32 v5, v5, 0x3d800000, v4
	v_fmac_f32_e32 v7, 0x3d800000, v6
	v_mul_f32_e32 v26, 0x3f317217, v29
	v_fma_f32 v26, v29, s45, -v26
	v_fmac_f32_e32 v26, 0x3377d1cf, v29
	v_fmac_f32_e32 v26, 0x3f317217, v29
	v_cmp_lt_f32_e64 s[42:43], |v29|, s47
	v_fmamk_f32 v8, v8, 0x3d800000, v7
	v_mul_f32_e32 v11, 0x3d800000, v11
	v_cndmask_b32_e64 v26, v29, v26, s[42:43]
	v_sub_f32_e32 v26, v26, v28
	v_sub_f32_e32 v17, v17, v26
	ds_bpermute_b32 v26, v48, v5
	v_fmamk_f32 v9, v9, 0x3d800000, v8
	v_fmac_f32_e32 v11, 0x3d800000, v10
	ds_bpermute_b32 v28, v48, v9
	v_fmamk_f32 v12, v12, 0x3d800000, v11
	v_mul_f32_e32 v15, 0x3d800000, v15
	v_fmamk_f32 v13, v13, 0x3d800000, v12
	s_waitcnt lgkmcnt(1)
	v_cndmask_b32_e64 v31, v26, 0, vcc
	v_fmac_f32_e32 v15, 0x3d800000, v14
	ds_bpermute_b32 v29, v48, v13
	v_add_f32_e32 v31, v27, v31
	v_fmamk_f32 v16, v16, 0x3d800000, v15
	v_fmamk_f32 v2, v2, 0x3d800000, v31
	v_add_f32_e32 v3, v31, v3
	v_add_f32_e32 v4, v31, v4
	v_add_f32_e32 v31, v31, v5
	v_add_f32_e32 v5, v5, v26
	v_fmamk_f32 v17, v17, 0x3d800000, v16
	v_add_f32_e32 v5, v27, v5
	s_waitcnt lgkmcnt(1)
	v_cndmask_b32_e64 v26, v28, 0, vcc
	ds_bpermute_b32 v30, v48, v17
	v_add_f32_e32 v26, v26, v5
	v_fmamk_f32 v6, v6, 0x3d800000, v26
	v_add_f32_e32 v7, v7, v26
	v_add_f32_e32 v8, v8, v26
	v_add_f32_e32 v26, v9, v26
	v_add_f32_e32 v9, v9, v28
	v_add_f32_e32 v5, v9, v5
	s_waitcnt lgkmcnt(1)
	v_cndmask_b32_e64 v9, v29, 0, vcc
	v_add_f32_e32 v9, v9, v5
	v_fmamk_f32 v10, v10, 0x3d800000, v9
	v_add_f32_e32 v11, v11, v9
	v_add_f32_e32 v12, v12, v9
	v_add_f32_e32 v9, v13, v9
	v_add_f32_e32 v13, v13, v29
	v_add_f32_e32 v5, v13, v5
	s_waitcnt lgkmcnt(0)
	v_cndmask_b32_e64 v13, v30, 0, vcc
	v_add_f32_e32 v5, v13, v5
	v_fmamk_f32 v13, v14, 0x3d800000, v5
	v_add_f32_e32 v14, v15, v5
	v_add_f32_e32 v15, v16, v5
	v_add_u32_e32 v16, 0x3000, v49
	ds_write2_b32 v16, v2, v3 offset1:96
	v_add_u32_e32 v2, 0x3200, v49
	ds_write2_b32 v2, v4, v31 offset0:64 offset1:160
	v_add_u32_e32 v2, 0x3c00, v49
	ds_write2_b32 v2, v6, v7 offset1:96
	v_add_u32_e32 v2, 0x3e00, v49
	ds_write2_b32 v2, v8, v26 offset0:64 offset1:160
	v_add_u32_e32 v2, 0x4800, v49
	ds_write2_b32 v2, v10, v11 offset1:96
	v_add_u32_e32 v2, 0x4a00, v49
	ds_write2_b32 v2, v12, v9 offset0:64 offset1:160
	v_add_u32_e32 v2, 0x5400, v49
	v_add_f32_e32 v5, v17, v5
	ds_write2_b32 v2, v13, v14 offset1:96
	v_add_u32_e32 v2, 0x5600, v49
	ds_write2_b32 v2, v15, v5 offset0:64 offset1:160

; #define DIL_LWRITE(RG) do { _Pragma("unroll") for (int i_ = 0; i_ < 6; ++i_) { const int c_ = tid + NTHR * i_, row_ = c_ >> 3, ch_ = c_ & 7; \
;         *(LAS u32x4*)(lds + DIL_KB + row_ * DIL_PITCH + 16 * ch_) = RG.k[i_]; *(LAS u32x4*)(lds + DIL_VB + row_ * DIL_PITCH + 16 * ch_) = RG.v[i_]; } } while (0)
; __global__ void __launch_bounds__(NTHR, 2) fwd_mega(Args args) {
;     ...
;                 for (int u = vcu; u < 4608; u += G) {
;                     const bool has_next = (u + G < 4608);
;                     DIL_LWRITE(RG);
;                     bf16x8 qf[4];
; #pragma unroll
;                     for (int d0 = 0; d0 < 4; ++d0) qf[d0] = RG.q[d0];
;                     __syncthreads();
;                     if (has_next) { DIL_MAKE(nxt, u + G); DIL_GLOAD(nxt, RG); }
.LBB0_522:
	s_add_i32 s7, s20, s92
	s_cmpk_gt_i32 s7, 0x11ff
	s_cselect_b64 s[14:15], -1, 0
	s_and_b64 vcc, exec, s[14:15]
	s_nop 0
	ds_write_b128 v141, v[54:57]
	s_nop 0
	ds_write_b128 v141, v[58:61] offset:55296
	ds_write_b128 v143, v[50:53]
	ds_write_b128 v143, v[62:65] offset:55296
	ds_write_b128 v148, v[70:73]
	ds_write_b128 v148, v[74:77] offset:55296
	ds_write_b128 v149, v[66:69]
	ds_write_b128 v149, v[78:81] offset:55296
	ds_write_b128 v150, v[82:85]
	ds_write_b128 v150, v[86:89] offset:55296
	ds_write_b128 v151, v[90:93]
	ds_write_b128 v151, v[94:97] offset:55296
	s_waitcnt lgkmcnt(0)
	s_barrier
	s_cbranch_vccnz .LBB0_529
	s_mul_hi_u32 s98, s7, 0x38e38f
	s_mul_i32 s99, s98, 0x480
	s_sub_i32 s99, s7, s99
	s_mul_hi_u32 s100, s99, 0xaaaaab
	s_mul_i32 s98, s98, 0x300
	s_sub_i32 s98, s7, s98
	s_mul_i32 s100, s100, 0x480
	s_add_i32 s99, s98, s100
	s_mul_hi_i32 s10, s99, 0x2aaaaaab
	s_lshr_b32 s11, s10, 31
	s_ashr_i32 s10, s10, 8
	s_add_i32 s11, s10, s11
	s_mul_i32 s10, s11, 0xfffffa00
	s_add_i32 s10, s10, s99
	s_mul_hi_i32 s16, s10, 0x2aaaaaab
	s_lshr_b32 s17, s16, 31
	s_ashr_i32 s16, s16, 1
	s_add_i32 s16, s16, s17
	s_mul_i32 s17, s16, -12
	s_add_i32 s10, s17, s10
	s_ashr_i32 s22, s16, 5
	s_and_b32 s21, s16, 31
	s_add_i32 s16, s99, 0x5ff
	s_cmpk_lt_u32 s16, 0xbff
	s_cselect_b64 s[26:27], -1, 0
	s_add_i32 s16, s99, 0xfffffa00
	s_cmpk_lt_u32 s16, 0x600
	s_cselect_b64 s[16:17], -1, 0
	s_and_b64 s[36:37], s[16:17], exec
	s_movk_i32 s30, 0x2400
	s_cselect_b32 s23, 2, 4
	s_cselect_b32 s30, s30, 0x9000
	s_and_b64 s[36:37], s[26:27], exec
	s_cselect_b32 s37, 0, s23
	s_sub_i32 s36, 5, s37
	s_lshr_b32 s23, 32, s37
	s_lshr_b32 s44, s21, s36
	s_mul_i32 s47, s44, s23
	s_sub_i32 s36, s21, s47
	s_ashr_i32 s23, s22, 31
	s_lshl_b64 s[42:43], s[22:23], 13
	s_lshl_b32 s22, s36, 8
	s_addk_i32 s22, 0xff80
	s_ashr_i32 s23, s22, 31
	s_or_b32 s42, s42, s44
	s_lshl_b64 s[22:23], s[22:23], s37
	s_add_u32 s37, s22, s42
	s_addc_u32 s49, s23, s43
	s_lshl_b32 s22, s10, 6
	s_ashr_i32 s23, s22, 31
	s_and_b64 s[44:45], s[26:27], exec
	s_mulk_i32 s49, 0x1200
	s_mul_hi_u32 s44, s37, 0x1200
	s_cselect_b32 s30, 0x900, s30
	s_add_i32 s44, s44, s49
	s_mulk_i32 s37, 0x1200
	s_add_u32 s37, s1, s37
	s_addc_u32 s45, s2, s44
	s_lshl_b64 s[22:23], s[22:23], 1
	s_add_u32 s44, s37, s22
	s_addc_u32 s45, s45, s23
	s_cmp_eq_u32 s21, s47
	s_cselect_b32 s21, 0x80, 0
	v_lshl_add_u64 v[2:3], s[44:45], 0, v[0:1]
	v_cmp_le_i32_e32 vcc, s21, v130
	s_and_saveexec_b64 s[44:45], vcc
	s_cbranch_execz .LBB0_530
	v_mad_u64_u32 v[4:5], s[50:51], s30, v130, 0
	v_lshl_add_u64 v[4:5], v[4:5], 1, v[2:3]
	global_load_dwordx4 v[54:57], v[4:5], off offset:1536
	global_load_dwordx4 v[58:61], v[4:5], off offset:3072
	s_or_b64 exec, exec, s[44:45]
	v_cmp_le_i32_e32 vcc, s21, v132
	s_and_saveexec_b64 s[44:45], vcc
	s_cbranch_execnz .LBB0_531

; DI void norm_row_out(const bf16* xrow, const float* g, float* orow, int lane) {
;     const u32x4* xr = (const u32x4*)xrow + lane; const f32x4* gr = (const f32x4*)g; f32x4* o4 = (f32x4*)orow;
;     float v[32]; float s = 0.f;
; #pragma unroll
;     for (int j = 0; j < 4; ++j) { const u32x4 w = xr[64 * j];
; #pragma unroll
;         for (int q = 0; q < 4; ++q) { v[8 * j + 2 * q] = bflo(w[q]); v[8 * j + 2 * q + 1] = bfhi(w[q]); s += v[8 * j + 2 * q] * v[8 * j + 2 * q] + v[8 * j + 2 * q + 1] * v[8 * j + 2 * q + 1]; } }
;     const float rstd = 1.f / sqrtf(wave_sum(s) * (1.f / D) + EPS);
; #pragma unroll
;     for (int j = 0; j < 4; ++j) { const int c4 = (64 * j + lane) * 2;
;         const f32x4 g0 = gr[c4], g1 = gr[c4 + 1];
;         o4[c4] = (f32x4){v[8 * j] * rstd * g0.x, v[8 * j + 1] * rstd * g0.y, v[8 * j + 2] * rstd * g0.z, v[8 * j + 3] * rstd * g0.w};
;         o4[c4 + 1] = (f32x4){v[8 * j + 4] * rstd * g1.x, v[8 * j + 5] * rstd * g1.y, v[8 * j + 6] * rstd * g1.z, v[8 * j + 7] * rstd * g1.w}; }
; __global__ void __launch_bounds__(NTHR, 2) fwd_mega(Args args) {
;     ...
;             for (int m = gw; m < T; m += NGW) norm_row_out(XN + (size_t)m * D, ap->in[I_NORMF], ap->out + (size_t)m * D, lane);
.LBB0_609:
	s_and_b64 vcc, exec, s[4:5]
	s_cbranch_vccz .LBB0_614
	s_cmpk_gt_i32 s46, 0x7fff
	s_cbranch_scc1 .LBB0_613
	v_add_u32_e32 v0, 64, v236
	s_waitcnt lgkmcnt(0)
	v_xor_b32_e32 v2, 1, v235
	v_cmp_lt_i32_e32 vcc, v2, v0
	s_load_dwordx2 s[4:5], s[82:83], 0x20
	v_mov_b32_e32 v3, v1
	v_cndmask_b32_e32 v2, v235, v2, vcc
	v_lshlrev_b32_e32 v54, 2, v2
	v_xor_b32_e32 v2, 2, v235
	v_cmp_lt_i32_e32 vcc, v2, v0
	s_ashr_i32 s47, s46, 31
	s_mov_b32 s1, s46
	v_cndmask_b32_e32 v2, v235, v2, vcc
	s_waitcnt vmcnt(0)
	v_lshlrev_b32_e32 v55, 2, v2
	v_xor_b32_e32 v2, 4, v235
	v_cmp_lt_i32_e32 vcc, v2, v0
	s_nop 1
	v_cndmask_b32_e32 v2, v235, v2, vcc
	v_lshlrev_b32_e32 v56, 2, v2
	v_xor_b32_e32 v2, 8, v235
	v_cmp_lt_i32_e32 vcc, v2, v0
	s_nop 1
	v_cndmask_b32_e32 v2, v235, v2, vcc
	v_lshlrev_b32_e32 v57, 2, v2
	v_xor_b32_e32 v2, 16, v235
	v_cmp_lt_i32_e32 vcc, v2, v0
	s_nop 1
	v_cndmask_b32_e32 v2, v235, v2, vcc
	v_lshlrev_b32_e32 v58, 2, v2
	v_xor_b32_e32 v2, 32, v235
	v_cmp_lt_i32_e32 vcc, v2, v0
	s_nop 1
	v_cndmask_b32_e32 v0, v235, v2, vcc
	v_lshlrev_b32_e32 v59, 2, v0
	v_lshlrev_b32_e32 v0, 5, v226
	v_or_b32_e32 v2, 0x1000, v0
	s_waitcnt lgkmcnt(0)
	v_lshl_add_u64 v[12:13], s[4:5], 0, v[2:3]
	v_or_b32_e32 v2, 0x1800, v0
	v_lshl_add_u64 v[10:11], s[4:5], 0, v[0:1]
	v_lshl_add_u64 v[14:15], s[4:5], 0, v[2:3]
	s_lshl_b64 s[4:5], s[46:47], 12
	s_add_u32 s4, s74, s4
	v_lshlrev_b32_e32 v2, 4, v226
	s_addc_u32 s5, s75, s5
	v_lshl_add_u64 v[2:3], s[4:5], 0, v[2:3]
	s_mov_b64 s[4:5], 0x7a00c00
	s_ashr_i32 s49, s48, 31
	v_lshl_add_u64 v[16:17], v[2:3], 0, s[4:5]
	s_lshl_b64 s[8:9], s[48:49], 12
	s_lshl_b64 s[4:5], s[46:47], 13
	s_add_u32 s4, s72, s4
	s_addc_u32 s5, s73, s5
	v_lshl_add_u64 v[2:3], s[4:5], 0, v[0:1]
	s_mov_b64 s[4:5], 0x1000
	v_lshl_add_u64 v[18:19], v[2:3], 0, s[4:5]
	s_lshl_b64 s[12:13], s[48:49], 13
	global_load_dwordx4 v[96:99], v[10:11], off
	global_load_dwordx4 v[100:103], v[10:11], off offset:16
	global_load_dwordx4 v[104:107], v[10:11], off offset:2048
	global_load_dwordx4 v[108:111], v[10:11], off offset:2064
	global_load_dwordx4 v[112:115], v[12:13], off
	global_load_dwordx4 v[116:119], v[12:13], off offset:16
	global_load_dwordx4 v[120:123], v[14:15], off
	global_load_dwordx4 v[124:127], v[14:15], off offset:16
	global_load_dwordx4 v[128:131], v[16:17], off offset:-3072
	global_load_dwordx4 v[132:135], v[16:17], off offset:-2048
	global_load_dwordx4 v[136:139], v[16:17], off offset:-1024
	global_load_dwordx4 v[140:143], v[16:17], off
	v_lshl_add_u64 v[16:17], v[16:17], 0, s[8:9]
	s_waitcnt vmcnt(0)
.LBB0_612:
	s_waitcnt vmcnt(8)
	v_mov_b32_e32 v24, v128
	v_mov_b32_e32 v25, v129
	v_mov_b32_e32 v26, v130
	v_mov_b32_e32 v27, v131
	v_mov_b32_e32 v28, v132
	v_mov_b32_e32 v29, v133
	v_mov_b32_e32 v30, v134
	v_mov_b32_e32 v31, v135
	v_mov_b32_e32 v60, v136
	v_mov_b32_e32 v61, v137
	v_mov_b32_e32 v62, v138
	v_mov_b32_e32 v63, v139
	v_mov_b32_e32 v64, v140
	v_mov_b32_e32 v65, v141
	v_mov_b32_e32 v66, v142
	v_mov_b32_e32 v67, v143
	s_add_i32 s1, s1, s48
	s_cmpk_gt_i32 s1, 0x7fff
	s_cbranch_scc1 .Lfnorm_nopf
	global_load_dwordx4 v[128:131], v[16:17], off offset:-3072
	global_load_dwordx4 v[132:135], v[16:17], off offset:-2048
	global_load_dwordx4 v[136:139], v[16:17], off offset:-1024
	global_load_dwordx4 v[140:143], v[16:17], off
	v_lshl_add_u64 v[16:17], v[16:17], 0, s[8:9]
; DI void norm_row_out(const bf16* xrow, const float* g, float* orow, int lane) {
;     const u32x4* xr = (const u32x4*)xrow + lane; const f32x4* gr = (const f32x4*)g; f32x4* o4 = (f32x4*)orow;
;     float v[32]; float s = 0.f;
; #pragma unroll
;     for (int j = 0; j < 4; ++j) { const u32x4 w = xr[64 * j];
; #pragma unroll
;         for (int q = 0; q < 4; ++q) { v[8 * j + 2 * q] = bflo(w[q]); v[8 * j + 2 * q + 1] = bfhi(w[q]); s += v[8 * j + 2 * q] * v[8 * j + 2 * q] + v[8 * j + 2 * q + 1] * v[8 * j + 2 * q + 1]; } }
;     const float rstd = 1.f / sqrtf(wave_sum(s) * (1.f / D) + EPS);
; #pragma unroll
;     for (int j = 0; j < 4; ++j) { const int c4 = (64 * j + lane) * 2;
;         const f32x4 g0 = gr[c4], g1 = gr[c4 + 1];
;         o4[c4] = (f32x4){v[8 * j] * rstd * g0.x, v[8 * j + 1] * rstd * g0.y, v[8 * j + 2] * rstd * g0.z, v[8 * j + 3] * rstd * g0.w};
;         o4[c4 + 1] = (f32x4){v[8 * j + 4] * rstd * g1.x, v[8 * j + 5] * rstd * g1.y, v[8 * j + 6] * rstd * g1.z, v[8 * j + 7] * rstd * g1.w}; }
.Lfnorm_nopf:
	v_lshlrev_b32_e32 v46, 16, v24
	v_and_b32_e32 v47, 0xffff0000, v24
	v_lshlrev_b32_e32 v50, 16, v25
	v_and_b32_e32 v51, 0xffff0000, v25
	v_lshlrev_b32_e32 v21, 16, v67
	v_lshlrev_b32_e32 v20, 16, v66
	v_and_b32_e32 v23, 0xffff0000, v67
	v_and_b32_e32 v22, 0xffff0000, v66
	v_pk_mul_f32 v[66:67], v[46:47], v[46:47]
	v_pk_mul_f32 v[68:69], v[50:51], v[50:51]
	v_lshlrev_b32_e32 v44, 16, v26
	v_and_b32_e32 v45, 0xffff0000, v26
	v_pk_mul_f32 v[70:71], v[44:45], v[44:45]
	v_lshlrev_b32_e32 v48, 16, v27
	v_and_b32_e32 v49, 0xffff0000, v27
	v_add_f32_e32 v68, v68, v69
	v_add_f32_e32 v66, v66, v67
	v_pk_mul_f32 v[2:3], v[22:23], v[22:23]
	v_pk_mul_f32 v[72:73], v[48:49], v[48:49]
	v_lshlrev_b32_e32 v38, 16, v28
	v_and_b32_e32 v39, 0xffff0000, v28
	v_add_f32_e32 v66, v66, v68
	v_add_f32_e32 v67, v70, v71
	v_pk_fma_f32 v[52:53], v[20:21], v[20:21], v[2:3]
	v_pk_mul_f32 v[74:75], v[38:39], v[38:39]
	v_lshlrev_b32_e32 v42, 16, v29
	v_and_b32_e32 v43, 0xffff0000, v29
	v_add_f32_e32 v0, v72, v73
	v_add_f32_e32 v66, v67, v66
	v_pk_mul_f32 v[76:77], v[42:43], v[42:43]
	v_lshlrev_b32_e32 v36, 16, v30
	v_and_b32_e32 v37, 0xffff0000, v30
	v_add_f32_e32 v0, v0, v66
	v_add_f32_e32 v66, v74, v75
	v_pk_mul_f32 v[78:79], v[36:37], v[36:37]
	v_lshlrev_b32_e32 v40, 16, v31
	v_and_b32_e32 v41, 0xffff0000, v31
	v_add_f32_e32 v0, v66, v0
	v_add_f32_e32 v66, v76, v77
	v_pk_mul_f32 v[80:81], v[40:41], v[40:41]
	v_lshlrev_b32_e32 v30, 16, v60
	v_and_b32_e32 v31, 0xffff0000, v60
	v_add_f32_e32 v0, v66, v0
	v_add_f32_e32 v66, v78, v79
	v_pk_mul_f32 v[82:83], v[30:31], v[30:31]
	v_lshlrev_b32_e32 v34, 16, v61
	v_and_b32_e32 v35, 0xffff0000, v61
	v_add_f32_e32 v0, v66, v0
	v_add_f32_e32 v66, v80, v81
	v_pk_mul_f32 v[60:61], v[34:35], v[34:35]
	v_lshlrev_b32_e32 v28, 16, v62
	v_and_b32_e32 v29, 0xffff0000, v62
	v_add_f32_e32 v0, v66, v0
	v_add_f32_e32 v66, v82, v83
	v_pk_mul_f32 v[84:85], v[28:29], v[28:29]
	v_lshlrev_b32_e32 v32, 16, v63
	v_and_b32_e32 v33, 0xffff0000, v63
	v_add_f32_e32 v0, v66, v0
	v_add_f32_e32 v60, v60, v61
	v_pk_mul_f32 v[62:63], v[32:33], v[32:33]
	v_lshlrev_b32_e32 v24, 16, v64
	v_and_b32_e32 v25, 0xffff0000, v64
	v_add_f32_e32 v0, v60, v0
	v_add_f32_e32 v60, v84, v85
	v_pk_mul_f32 v[86:87], v[24:25], v[24:25]
	v_lshlrev_b32_e32 v26, 16, v65
	v_and_b32_e32 v27, 0xffff0000, v65
	v_add_f32_e32 v0, v60, v0
	v_add_f32_e32 v60, v62, v63
	v_pk_mul_f32 v[64:65], v[26:27], v[26:27]
	v_add_f32_e32 v0, v60, v0
	v_add_f32_e32 v60, v86, v87
	v_add_f32_e32 v0, v60, v0
	v_add_f32_e32 v60, v64, v65
	v_add_f32_e32 v0, v60, v0
	v_add_f32_e32 v0, v52, v0
	v_add_f32_e32 v0, v53, v0
	ds_bpermute_b32 v52, v54, v0
	s_waitcnt lgkmcnt(0)
	v_add_f32_e32 v0, v0, v52
	ds_bpermute_b32 v52, v55, v0
	s_waitcnt lgkmcnt(0)
	v_add_f32_e32 v0, v0, v52
	ds_bpermute_b32 v52, v56, v0
	s_waitcnt lgkmcnt(0)
	v_add_f32_e32 v0, v0, v52
	ds_bpermute_b32 v52, v57, v0
	s_waitcnt lgkmcnt(0)
	v_add_f32_e32 v0, v0, v52
	ds_bpermute_b32 v52, v58, v0
	s_waitcnt lgkmcnt(0)
	v_add_f32_e32 v0, v0, v52
	ds_bpermute_b32 v52, v59, v0
	s_waitcnt lgkmcnt(0)
	v_add_f32_e32 v0, v0, v52
	v_fmamk_f32 v0, v0, 0x3a000000, v232
	v_cmp_gt_f32_e32 vcc, s94, v0
	v_mul_f32_e32 v52, 0x4f800000, v0
	s_nop 0
	v_cndmask_b32_e32 v0, v0, v52, vcc
	v_sqrt_f32_e32 v52, v0
	s_nop 0
	v_add_u32_e32 v53, -1, v52
	v_fma_f32 v60, -v53, v52, v0
	v_cmp_ge_f32_e64 s[40:41], 0, v60
	v_add_u32_e32 v60, 1, v52
	s_nop 0
	v_cndmask_b32_e64 v53, v52, v53, s[40:41]
	v_fma_f32 v52, -v60, v52, v0
	v_cmp_lt_f32_e64 s[40:41], 0, v52
	s_nop 1
	v_cndmask_b32_e64 v52, v53, v60, s[40:41]
	v_mul_f32_e32 v53, 0x37800000, v52
	v_cndmask_b32_e32 v52, v52, v53, vcc
	v_cmp_class_f32_e32 vcc, v0, v233
	s_nop 1
	v_cndmask_b32_e32 v0, v52, v0, vcc
	v_div_scale_f32 v52, s[4:5], v0, v0, 1.0
	v_rcp_f32_e32 v53, v52
	s_nop 0
	v_fma_f32 v60, -v52, v53, 1.0
	v_fmac_f32_e32 v53, v60, v53
	v_div_scale_f32 v60, vcc, 1.0, v0, 1.0
	v_mul_f32_e32 v61, v60, v53
	v_fma_f32 v62, -v52, v61, v60
	v_fmac_f32_e32 v61, v62, v53
	v_fma_f32 v52, -v52, v61, v60
	v_div_fmas_f32 v52, v52, v53, v61
	v_div_fixup_f32 v0, v52, v0, 1.0
	v_pk_mul_f32 v[46:47], v[0:1], v[46:47] op_sel_hi:[0,1]
	v_pk_mul_f32 v[50:51], v[0:1], v[50:51] op_sel_hi:[0,1]
	s_nop 0
	v_pk_mul_f32 v[8:9], v[98:99], v[50:51]
	v_pk_mul_f32 v[6:7], v[96:97], v[46:47]
	global_store_dwordx4 v[18:19], v[6:9], off offset:-4096
	v_pk_mul_f32 v[42:43], v[0:1], v[42:43] op_sel_hi:[0,1]
	v_pk_mul_f32 v[38:39], v[0:1], v[38:39] op_sel_hi:[0,1]
	v_pk_mul_f32 v[6:7], v[0:1], v[44:45] op_sel_hi:[0,1]
	v_pk_mul_f32 v[8:9], v[0:1], v[48:49] op_sel_hi:[0,1]
	v_pk_mul_f32 v[4:5], v[102:103], v[8:9]
	v_pk_mul_f32 v[2:3], v[100:101], v[6:7]
	global_store_dwordx4 v[18:19], v[2:5], off offset:-4080
	v_pk_mul_f32 v[34:35], v[0:1], v[34:35] op_sel_hi:[0,1]
	v_pk_mul_f32 v[30:31], v[0:1], v[30:31] op_sel_hi:[0,1]
	v_pk_mul_f32 v[26:27], v[0:1], v[26:27] op_sel_hi:[0,1]
	v_pk_mul_f32 v[24:25], v[0:1], v[24:25] op_sel_hi:[0,1]
	s_nop 0
	v_pk_mul_f32 v[6:7], v[104:105], v[38:39]
	v_pk_mul_f32 v[8:9], v[106:107], v[42:43]
	global_store_dwordx4 v[18:19], v[6:9], off offset:-2048
	s_nop 1
	v_pk_mul_f32 v[6:7], v[0:1], v[40:41] op_sel_hi:[0,1]
	v_pk_mul_f32 v[8:9], v[0:1], v[36:37] op_sel_hi:[0,1]
	v_pk_mul_f32 v[2:3], v[108:109], v[8:9]
	v_pk_mul_f32 v[4:5], v[110:111], v[6:7]
	global_store_dwordx4 v[18:19], v[2:5], off offset:-2032
	s_nop 0
	v_pk_mul_f32 v[6:7], v[112:113], v[30:31]
	v_pk_mul_f32 v[8:9], v[114:115], v[34:35]
	global_store_dwordx4 v[18:19], v[6:9], off
	s_nop 1
	v_pk_mul_f32 v[6:7], v[0:1], v[32:33] op_sel_hi:[0,1]
	v_pk_mul_f32 v[8:9], v[0:1], v[28:29] op_sel_hi:[0,1]
	v_pk_mul_f32 v[2:3], v[116:117], v[8:9]
	v_pk_mul_f32 v[4:5], v[118:119], v[6:7]
	global_store_dwordx4 v[18:19], v[2:5], off offset:16
	s_nop 0
	v_pk_mul_f32 v[6:7], v[120:121], v[24:25]
	v_pk_mul_f32 v[8:9], v[122:123], v[26:27]
	global_store_dwordx4 v[18:19], v[6:9], off offset:2048
	s_nop 1
	v_mov_b32_e32 v6, v20
	v_mov_b32_e32 v7, v22
	v_pk_mul_f32 v[6:7], v[0:1], v[6:7] op_sel_hi:[0,1]
	v_mov_b32_e32 v22, v21
	v_pk_mul_f32 v[2:3], v[124:125], v[6:7]
	v_pk_mul_f32 v[6:7], v[0:1], v[22:23] op_sel_hi:[0,1]
	v_pk_mul_f32 v[4:5], v[126:127], v[6:7]
	global_store_dwordx4 v[18:19], v[2:5], off offset:2064
	v_lshl_add_u64 v[18:19], v[18:19], 0, s[12:13]
	s_cbranch_scc0 .LBB0_612
